# v066 + ds_reads hoisted to the top of every LOAD segment (SALU pointer math and DMA setup after), s_nop 0 added where m0 write now directly precedes an LDS-DMA load
# baseline (speedup 1.0000x reference)
.LBB0_491:
	s_add_i32 s54, 0, 0x10000
	s_add_i32 s56, 0, 0x14000
	v_add_u32_e32 v156, s54, v141
	v_add_u32_e32 v172, s56, v141
	ds_read_b128 v[144:147], v156
	ds_read_b128 v[148:151], v156 offset:1024
	ds_read_b128 v[152:155], v156 offset:2048
	ds_read_b128 v[156:159], v156 offset:3072
	ds_read_b128 v[160:163], v172
	ds_read_b128 v[164:167], v172 offset:1024
	ds_read_b128 v[168:171], v172 offset:2048
	ds_read_b128 v[172:175], v172 offset:3072
	ds_read_b128 v[176:179], v143
	ds_read_b128 v[180:183], v143 offset:1024
	ds_read_b128 v[184:187], v143 offset:2048
	ds_read_b128 v[188:191], v143 offset:3072
	ds_read_b128 v[192:195], v143 offset:4096
	ds_read_b128 v[196:199], v143 offset:5120
	ds_read_b128 v[200:203], v143 offset:6144
	ds_read_b128 v[204:207], v143 offset:7168
	s_add_u32 s18, s16, 0xfff80080
	s_addc_u32 s19, s17, -1
	s_cmp_eq_u32 s53, 28
	s_cselect_b32 s21, s11, s19
	s_cselect_b32 s20, s49, s18
	s_cselect_b32 s19, s9, s52
	s_cselect_b32 s18, s50, s51
	v_lshl_add_u64 v[208:209], s[16:17], 0, v[136:137]
	s_add_i32 m0, s39, 0xc000
	s_nop 0
	global_load_lds_dwordx4 v[208:209], off
	v_lshl_add_u64 v[208:209], s[16:17], 0, v[138:139]
	s_add_i32 m0, s39, 0xe000
	s_nop 0
	global_load_lds_dwordx4 v[208:209], off
	s_waitcnt vmcnt(8)
	s_waitcnt lgkmcnt(0)
	s_setprio 1
	s_barrier
	v_mfma_f32_16x16x32_bf16 v[126:129], v[144:147], v[176:179], v[126:129]
	v_mfma_f32_16x16x32_bf16 v[122:125], v[152:155], v[176:179], v[122:125]
	v_mfma_f32_16x16x32_bf16 v[118:121], v[144:147], v[184:187], v[118:121]
	v_mfma_f32_16x16x32_bf16 v[114:117], v[152:155], v[184:187], v[114:117]
	v_mfma_f32_16x16x32_bf16 v[102:105], v[144:147], v[192:195], v[102:105]
	v_mfma_f32_16x16x32_bf16 v[98:101], v[152:155], v[192:195], v[98:101]
	v_mfma_f32_16x16x32_bf16 v[86:89], v[144:147], v[200:203], v[86:89]
	v_mfma_f32_16x16x32_bf16 v[82:85], v[152:155], v[200:203], v[82:85]
	v_mfma_f32_16x16x32_bf16 v[126:129], v[148:151], v[180:183], v[126:129]
	v_mfma_f32_16x16x32_bf16 v[122:125], v[156:159], v[180:183], v[122:125]
	v_mfma_f32_16x16x32_bf16 v[118:121], v[148:151], v[188:191], v[118:121]
	v_mfma_f32_16x16x32_bf16 v[114:117], v[156:159], v[188:191], v[114:117]
	v_mfma_f32_16x16x32_bf16 v[102:105], v[148:151], v[196:199], v[102:105]
	v_mfma_f32_16x16x32_bf16 v[98:101], v[156:159], v[196:199], v[98:101]
	v_mfma_f32_16x16x32_bf16 v[86:89], v[148:151], v[204:207], v[86:89]
	v_mfma_f32_16x16x32_bf16 v[82:85], v[156:159], v[204:207], v[82:85]
	s_setprio 0
	s_setprio 1
	v_mfma_f32_16x16x32_bf16 v[110:113], v[160:163], v[176:179], v[110:113]
	v_mfma_f32_16x16x32_bf16 v[106:109], v[168:171], v[176:179], v[106:109]
	v_mfma_f32_16x16x32_bf16 v[94:97], v[160:163], v[184:187], v[94:97]
	v_mfma_f32_16x16x32_bf16 v[90:93], v[168:171], v[184:187], v[90:93]
	v_mfma_f32_16x16x32_bf16 v[78:81], v[160:163], v[192:195], v[78:81]
	v_mfma_f32_16x16x32_bf16 v[74:77], v[168:171], v[192:195], v[74:77]
	v_mfma_f32_16x16x32_bf16 v[70:73], v[160:163], v[200:203], v[70:73]
	v_mfma_f32_16x16x32_bf16 v[66:69], v[168:171], v[200:203], v[66:69]
	v_mfma_f32_16x16x32_bf16 v[110:113], v[164:167], v[180:183], v[110:113]
	v_mfma_f32_16x16x32_bf16 v[106:109], v[172:175], v[180:183], v[106:109]
	v_mfma_f32_16x16x32_bf16 v[94:97], v[164:167], v[188:191], v[94:97]
	v_mfma_f32_16x16x32_bf16 v[90:93], v[172:175], v[188:191], v[90:93]
	v_mfma_f32_16x16x32_bf16 v[78:81], v[164:167], v[196:199], v[78:81]
	v_mfma_f32_16x16x32_bf16 v[74:77], v[172:175], v[196:199], v[74:77]
	v_mfma_f32_16x16x32_bf16 v[70:73], v[164:167], v[204:207], v[70:73]
	v_mfma_f32_16x16x32_bf16 v[66:69], v[172:175], v[204:207], v[66:69]
	s_barrier
	s_setprio 0
	ds_read_b128 v[176:179], v143 offset:16384
	ds_read_b128 v[180:183], v143 offset:17408
	ds_read_b128 v[184:187], v143 offset:18432
	ds_read_b128 v[188:191], v143 offset:19456
	ds_read_b128 v[192:195], v143 offset:20480
	ds_read_b128 v[196:199], v143 offset:21504
	ds_read_b128 v[200:203], v143 offset:22528
	ds_read_b128 v[204:207], v143 offset:23552
	s_add_i32 s54, s54, s37
	v_lshl_add_u64 v[208:209], s[18:19], 0, v[0:1]
	s_mov_b32 m0, s54
	s_nop 0
	global_load_lds_dwordx4 v[208:209], off
	s_add_i32 m0, s54, 0x2000
	s_add_u32 s54, s18, 0x80000
	v_lshl_add_u64 v[220:221], s[18:19], 0, v[130:131]
	s_addc_u32 s55, s19, 0
	s_add_i32 s56, s56, s37
	global_load_lds_dwordx4 v[220:221], off
	v_lshl_add_u64 v[222:223], s[54:55], 0, v[0:1]
	s_mov_b32 m0, s56
	v_lshl_add_u64 v[224:225], s[20:21], 0, v[132:133]
	global_load_lds_dwordx4 v[222:223], off
	v_lshl_add_u64 v[222:223], s[54:55], 0, v[130:131]
	s_add_i32 m0, s56, 0x2000
	s_nop 0
	global_load_lds_dwordx4 v[222:223], off
	v_lshl_add_u64 v[222:223], s[20:21], 0, v[134:135]
	s_mov_b32 m0, s39
	s_nop 0
	global_load_lds_dwordx4 v[222:223], off
	s_mov_b32 m0, s40
	s_nop 0
	global_load_lds_dwordx4 v[224:225], off
	s_waitcnt vmcnt(8)
	s_waitcnt lgkmcnt(0)
	s_setprio 1
	s_barrier
	v_mfma_f32_16x16x32_bf16 v[62:65], v[144:147], v[176:179], v[62:65]
	v_mfma_f32_16x16x32_bf16 v[58:61], v[152:155], v[176:179], v[58:61]
	v_mfma_f32_16x16x32_bf16 v[54:57], v[144:147], v[184:187], v[54:57]
	v_mfma_f32_16x16x32_bf16 v[50:53], v[152:155], v[184:187], v[50:53]
	v_mfma_f32_16x16x32_bf16 v[38:41], v[144:147], v[192:195], v[38:41]
	v_mfma_f32_16x16x32_bf16 v[34:37], v[152:155], v[192:195], v[34:37]
	v_mfma_f32_16x16x32_bf16 v[22:25], v[144:147], v[200:203], v[22:25]
	v_mfma_f32_16x16x32_bf16 v[18:21], v[152:155], v[200:203], v[18:21]
	v_mfma_f32_16x16x32_bf16 v[62:65], v[148:151], v[180:183], v[62:65]
	v_mfma_f32_16x16x32_bf16 v[58:61], v[156:159], v[180:183], v[58:61]
	v_mfma_f32_16x16x32_bf16 v[54:57], v[148:151], v[188:191], v[54:57]
	v_mfma_f32_16x16x32_bf16 v[50:53], v[156:159], v[188:191], v[50:53]
	v_mfma_f32_16x16x32_bf16 v[38:41], v[148:151], v[196:199], v[38:41]
	v_mfma_f32_16x16x32_bf16 v[34:37], v[156:159], v[196:199], v[34:37]
	v_mfma_f32_16x16x32_bf16 v[22:25], v[148:151], v[204:207], v[22:25]
	v_mfma_f32_16x16x32_bf16 v[18:21], v[156:159], v[204:207], v[18:21]
	s_setprio 0
	s_setprio 1
	v_mfma_f32_16x16x32_bf16 v[46:49], v[160:163], v[176:179], v[46:49]
	v_mfma_f32_16x16x32_bf16 v[42:45], v[168:171], v[176:179], v[42:45]
	v_mfma_f32_16x16x32_bf16 v[30:33], v[160:163], v[184:187], v[30:33]
	v_mfma_f32_16x16x32_bf16 v[26:29], v[168:171], v[184:187], v[26:29]
	v_mfma_f32_16x16x32_bf16 v[14:17], v[160:163], v[192:195], v[14:17]
	v_mfma_f32_16x16x32_bf16 v[10:13], v[168:171], v[192:195], v[10:13]
	v_mfma_f32_16x16x32_bf16 v[6:9], v[160:163], v[200:203], v[6:9]
	v_mfma_f32_16x16x32_bf16 v[2:5], v[168:171], v[200:203], v[2:5]
	v_mfma_f32_16x16x32_bf16 v[46:49], v[164:167], v[180:183], v[46:49]
	v_mfma_f32_16x16x32_bf16 v[42:45], v[172:175], v[180:183], v[42:45]
	v_mfma_f32_16x16x32_bf16 v[30:33], v[164:167], v[188:191], v[30:33]
	v_mfma_f32_16x16x32_bf16 v[26:29], v[172:175], v[188:191], v[26:29]
	v_mfma_f32_16x16x32_bf16 v[14:17], v[164:167], v[196:199], v[14:17]
	v_mfma_f32_16x16x32_bf16 v[10:13], v[172:175], v[196:199], v[10:13]
	v_mfma_f32_16x16x32_bf16 v[6:9], v[164:167], v[204:207], v[6:9]
	v_mfma_f32_16x16x32_bf16 v[2:5], v[172:175], v[204:207], v[2:5]
	s_barrier
	s_setprio 0
	s_add_i32 s54, 0, 0x18000
	s_add_i32 s55, 0, 0x1c000
	v_add_u32_e32 v156, s54, v141
	v_add_u32_e32 v172, s55, v141
	ds_read_b128 v[144:147], v156
	ds_read_b128 v[148:151], v156 offset:1024
	ds_read_b128 v[152:155], v156 offset:2048
	ds_read_b128 v[156:159], v156 offset:3072
	ds_read_b128 v[160:163], v172
	ds_read_b128 v[164:167], v172 offset:1024
	ds_read_b128 v[168:171], v172 offset:2048
	ds_read_b128 v[172:175], v172 offset:3072
	ds_read_b128 v[176:179], v143 offset:32768
	ds_read_b128 v[180:183], v143 offset:33792
	ds_read_b128 v[184:187], v143 offset:34816
	ds_read_b128 v[188:191], v143 offset:35840
	ds_read_b128 v[192:195], v143 offset:36864
	ds_read_b128 v[196:199], v143 offset:37888
	ds_read_b128 v[200:203], v143 offset:38912
	ds_read_b128 v[204:207], v143 offset:39936
	s_add_u32 s20, s20, 0x80000
	s_addc_u32 s21, s21, 0
	s_mov_b32 m0, s41
	v_lshl_add_u64 v[226:227], s[20:21], 0, v[134:135]
	global_load_lds_dwordx4 v[226:227], off
	v_lshl_add_u64 v[226:227], s[20:21], 0, v[132:133]
	s_mov_b32 m0, s44
	s_nop 0
	global_load_lds_dwordx4 v[226:227], off
	s_waitcnt vmcnt(8)
	s_waitcnt lgkmcnt(0)
	s_setprio 1
	s_barrier
	v_mfma_f32_16x16x32_bf16 v[126:129], v[144:147], v[176:179], v[126:129]
	v_mfma_f32_16x16x32_bf16 v[122:125], v[152:155], v[176:179], v[122:125]
	v_mfma_f32_16x16x32_bf16 v[118:121], v[144:147], v[184:187], v[118:121]
	v_mfma_f32_16x16x32_bf16 v[114:117], v[152:155], v[184:187], v[114:117]
	v_mfma_f32_16x16x32_bf16 v[102:105], v[144:147], v[192:195], v[102:105]
	v_mfma_f32_16x16x32_bf16 v[98:101], v[152:155], v[192:195], v[98:101]
	v_mfma_f32_16x16x32_bf16 v[86:89], v[144:147], v[200:203], v[86:89]
	v_mfma_f32_16x16x32_bf16 v[82:85], v[152:155], v[200:203], v[82:85]
	v_mfma_f32_16x16x32_bf16 v[126:129], v[148:151], v[180:183], v[126:129]
	v_mfma_f32_16x16x32_bf16 v[122:125], v[156:159], v[180:183], v[122:125]
	v_mfma_f32_16x16x32_bf16 v[118:121], v[148:151], v[188:191], v[118:121]
	v_mfma_f32_16x16x32_bf16 v[114:117], v[156:159], v[188:191], v[114:117]
	v_mfma_f32_16x16x32_bf16 v[102:105], v[148:151], v[196:199], v[102:105]
	v_mfma_f32_16x16x32_bf16 v[98:101], v[156:159], v[196:199], v[98:101]
	v_mfma_f32_16x16x32_bf16 v[86:89], v[148:151], v[204:207], v[86:89]
	v_mfma_f32_16x16x32_bf16 v[82:85], v[156:159], v[204:207], v[82:85]
	s_setprio 0
	s_setprio 1
	v_mfma_f32_16x16x32_bf16 v[110:113], v[160:163], v[176:179], v[110:113]
	v_mfma_f32_16x16x32_bf16 v[106:109], v[168:171], v[176:179], v[106:109]
	v_mfma_f32_16x16x32_bf16 v[94:97], v[160:163], v[184:187], v[94:97]
	v_mfma_f32_16x16x32_bf16 v[90:93], v[168:171], v[184:187], v[90:93]
	v_mfma_f32_16x16x32_bf16 v[78:81], v[160:163], v[192:195], v[78:81]
	v_mfma_f32_16x16x32_bf16 v[74:77], v[168:171], v[192:195], v[74:77]
	v_mfma_f32_16x16x32_bf16 v[70:73], v[160:163], v[200:203], v[70:73]
	v_mfma_f32_16x16x32_bf16 v[66:69], v[168:171], v[200:203], v[66:69]
	v_mfma_f32_16x16x32_bf16 v[110:113], v[164:167], v[180:183], v[110:113]
	v_mfma_f32_16x16x32_bf16 v[106:109], v[172:175], v[180:183], v[106:109]
	v_mfma_f32_16x16x32_bf16 v[94:97], v[164:167], v[188:191], v[94:97]
	v_mfma_f32_16x16x32_bf16 v[90:93], v[172:175], v[188:191], v[90:93]
	v_mfma_f32_16x16x32_bf16 v[78:81], v[164:167], v[196:199], v[78:81]
	v_mfma_f32_16x16x32_bf16 v[74:77], v[172:175], v[196:199], v[74:77]
	v_mfma_f32_16x16x32_bf16 v[70:73], v[164:167], v[204:207], v[70:73]
	v_mfma_f32_16x16x32_bf16 v[66:69], v[172:175], v[204:207], v[66:69]
	s_barrier
	s_setprio 0
	ds_read_b128 v[176:179], v143 offset:49152
	ds_read_b128 v[180:183], v143 offset:50176
	ds_read_b128 v[184:187], v143 offset:51200
	ds_read_b128 v[188:191], v143 offset:52224
	ds_read_b128 v[192:195], v143 offset:53248
	ds_read_b128 v[196:199], v143 offset:54272
	ds_read_b128 v[200:203], v143 offset:55296
	ds_read_b128 v[204:207], v143 offset:56320
	s_add_i32 s20, s54, s37
	v_lshl_add_u64 v[208:209], v[208:209], 0, s[2:3]
	s_mov_b32 m0, s20
	s_nop 0
	global_load_lds_dwordx4 v[208:209], off
	s_add_i32 m0, s20, 0x2000
	s_add_u32 s18, s18, 0x80080
	v_lshl_add_u64 v[208:209], v[220:221], 0, s[2:3]
	s_addc_u32 s19, s19, 0
	s_add_i32 s20, s55, s37
	global_load_lds_dwordx4 v[208:209], off
	v_lshl_add_u64 v[208:209], s[18:19], 0, v[0:1]
	s_mov_b32 m0, s20
	s_nop 0
	global_load_lds_dwordx4 v[208:209], off
	v_lshl_add_u64 v[208:209], s[18:19], 0, v[130:131]
	s_add_i32 m0, s20, 0x2000
	s_nop 0
	global_load_lds_dwordx4 v[208:209], off
	v_lshl_add_u64 v[208:209], v[222:223], 0, s[2:3]
	s_mov_b32 m0, s45
	s_nop 0
	global_load_lds_dwordx4 v[208:209], off
	v_lshl_add_u64 v[208:209], v[224:225], 0, s[2:3]
	s_mov_b32 m0, s46
	s_nop 0
	global_load_lds_dwordx4 v[208:209], off
	s_waitcnt vmcnt(8)
	s_waitcnt lgkmcnt(0)
	s_setprio 1
	s_barrier
	v_mfma_f32_16x16x32_bf16 v[62:65], v[144:147], v[176:179], v[62:65]
	v_mfma_f32_16x16x32_bf16 v[58:61], v[152:155], v[176:179], v[58:61]
	v_mfma_f32_16x16x32_bf16 v[54:57], v[144:147], v[184:187], v[54:57]
	v_mfma_f32_16x16x32_bf16 v[50:53], v[152:155], v[184:187], v[50:53]
	v_mfma_f32_16x16x32_bf16 v[38:41], v[144:147], v[192:195], v[38:41]
	v_mfma_f32_16x16x32_bf16 v[34:37], v[152:155], v[192:195], v[34:37]
	v_mfma_f32_16x16x32_bf16 v[22:25], v[144:147], v[200:203], v[22:25]
	v_mfma_f32_16x16x32_bf16 v[18:21], v[152:155], v[200:203], v[18:21]
	v_mfma_f32_16x16x32_bf16 v[62:65], v[148:151], v[180:183], v[62:65]
	v_mfma_f32_16x16x32_bf16 v[58:61], v[156:159], v[180:183], v[58:61]
	v_mfma_f32_16x16x32_bf16 v[54:57], v[148:151], v[188:191], v[54:57]
	v_mfma_f32_16x16x32_bf16 v[50:53], v[156:159], v[188:191], v[50:53]
	v_mfma_f32_16x16x32_bf16 v[38:41], v[148:151], v[196:199], v[38:41]
	v_mfma_f32_16x16x32_bf16 v[34:37], v[156:159], v[196:199], v[34:37]
	v_mfma_f32_16x16x32_bf16 v[22:25], v[148:151], v[204:207], v[22:25]
	v_mfma_f32_16x16x32_bf16 v[18:21], v[156:159], v[204:207], v[18:21]
	s_setprio 0
	s_setprio 1
	v_mfma_f32_16x16x32_bf16 v[46:49], v[160:163], v[176:179], v[46:49]
	v_mfma_f32_16x16x32_bf16 v[42:45], v[168:171], v[176:179], v[42:45]
	v_mfma_f32_16x16x32_bf16 v[30:33], v[160:163], v[184:187], v[30:33]
	v_mfma_f32_16x16x32_bf16 v[26:29], v[168:171], v[184:187], v[26:29]
	v_mfma_f32_16x16x32_bf16 v[14:17], v[160:163], v[192:195], v[14:17]
	v_mfma_f32_16x16x32_bf16 v[10:13], v[168:171], v[192:195], v[10:13]
	v_mfma_f32_16x16x32_bf16 v[6:9], v[160:163], v[200:203], v[6:9]
	v_mfma_f32_16x16x32_bf16 v[2:5], v[168:171], v[200:203], v[2:5]
	v_mfma_f32_16x16x32_bf16 v[46:49], v[164:167], v[180:183], v[46:49]
	v_mfma_f32_16x16x32_bf16 v[42:45], v[172:175], v[180:183], v[42:45]
	v_mfma_f32_16x16x32_bf16 v[30:33], v[164:167], v[188:191], v[30:33]
	v_mfma_f32_16x16x32_bf16 v[26:29], v[172:175], v[188:191], v[26:29]
	v_mfma_f32_16x16x32_bf16 v[14:17], v[164:167], v[196:199], v[14:17]
	v_mfma_f32_16x16x32_bf16 v[10:13], v[172:175], v[196:199], v[10:13]
	v_mfma_f32_16x16x32_bf16 v[6:9], v[164:167], v[204:207], v[6:9]
	v_mfma_f32_16x16x32_bf16 v[2:5], v[172:175], v[204:207], v[2:5]
	s_barrier
	s_setprio 0
	s_add_i32 s53, s53, 2
	s_add_u32 s16, s16, 0x100
	s_addc_u32 s17, s17, 0
	s_add_u32 s51, s51, 0x100
	s_addc_u32 s52, s52, 0
	s_cmp_gt_u32 s53, 29
	s_cbranch_scc0 .LBB0_491

.LBB0_883:
	s_add_i32 s44, 0, 0x10000
	v_add_u32_e32 v0, s44, v224
	s_add_i32 s45, 0, 0x14000
	ds_read_b128 v[30:33], v0
	ds_read_b128 v[134:137], v0 offset:1024
	ds_read_b128 v[138:141], v0 offset:2048
	ds_read_b128 v[142:145], v0 offset:3072
	v_add_u32_e32 v0, s45, v224
	ds_read_b128 v[146:149], v0
	ds_read_b128 v[150:153], v0 offset:1024
	ds_read_b128 v[154:157], v0 offset:2048
	ds_read_b128 v[158:161], v0 offset:3072
	ds_read_b128 v[162:165], v225
	ds_read_b128 v[166:169], v225 offset:1024
	ds_read_b128 v[170:173], v225 offset:2048
	ds_read_b128 v[174:177], v225 offset:3072
	ds_read_b128 v[178:181], v225 offset:4096
	ds_read_b128 v[182:185], v225 offset:5120
	ds_read_b128 v[186:189], v225 offset:6144
	ds_read_b128 v[190:193], v225 offset:7168
	s_add_i32 s41, s22, 2
	s_add_u32 s42, s38, 0xfff80080
	s_addc_u32 s23, s39, -1
	s_cmp_eq_u32 s63, s22
	s_cselect_b32 s23, s17, s23
	s_cselect_b32 s22, s16, s42
	s_cselect_b32 s43, s19, s21
	s_cselect_b32 s42, s18, s15
	v_lshl_add_u64 v[206:207], s[38:39], 0, v[202:203]
	s_add_i32 m0, s52, 0xc000
	s_nop 0
	global_load_lds_dwordx4 v[206:207], off
	v_lshl_add_u64 v[206:207], s[38:39], 0, v[204:205]
	s_add_i32 m0, s52, 0xe000
	s_nop 0
	global_load_lds_dwordx4 v[206:207], off
	s_waitcnt vmcnt(8)
	s_waitcnt lgkmcnt(0)
	s_setprio 1
	s_barrier
	v_mfma_f32_16x16x32_bf16 v[26:29], v[30:33], v[162:165], v[26:29]
	v_mfma_f32_16x16x32_bf16 v[22:25], v[138:141], v[162:165], v[22:25]
	v_mfma_f32_16x16x32_bf16 v[62:65], v[30:33], v[170:173], v[62:65]
	v_mfma_f32_16x16x32_bf16 v[14:17], v[138:141], v[170:173], v[14:17]
	v_mfma_f32_16x16x32_bf16 v[58:61], v[30:33], v[178:181], v[58:61]
	v_mfma_f32_16x16x32_bf16 v[54:57], v[138:141], v[178:181], v[54:57]
	v_mfma_f32_16x16x32_bf16 v[94:97], v[30:33], v[186:189], v[94:97]
	v_mfma_f32_16x16x32_bf16 v[46:49], v[138:141], v[186:189], v[46:49]
	v_mfma_f32_16x16x32_bf16 v[26:29], v[134:137], v[166:169], v[26:29]
	v_mfma_f32_16x16x32_bf16 v[22:25], v[142:145], v[166:169], v[22:25]
	v_mfma_f32_16x16x32_bf16 v[62:65], v[134:137], v[174:177], v[62:65]
	v_mfma_f32_16x16x32_bf16 v[14:17], v[142:145], v[174:177], v[14:17]
	v_mfma_f32_16x16x32_bf16 v[58:61], v[134:137], v[182:185], v[58:61]
	v_mfma_f32_16x16x32_bf16 v[54:57], v[142:145], v[182:185], v[54:57]
	v_mfma_f32_16x16x32_bf16 v[94:97], v[134:137], v[190:193], v[94:97]
	v_mfma_f32_16x16x32_bf16 v[46:49], v[142:145], v[190:193], v[46:49]
	s_setprio 0
	s_setprio 1
	v_mfma_f32_16x16x32_bf16 v[18:21], v[146:149], v[162:165], v[18:21]
	v_mfma_f32_16x16x32_bf16 v[10:13], v[154:157], v[162:165], v[10:13]
	v_mfma_f32_16x16x32_bf16 v[2:5], v[146:149], v[170:173], v[2:5]
	v_mfma_f32_16x16x32_bf16 v[6:9], v[154:157], v[170:173], v[6:9]
	v_mfma_f32_16x16x32_bf16 v[50:53], v[146:149], v[178:181], v[50:53]
	v_mfma_f32_16x16x32_bf16 v[42:45], v[154:157], v[178:181], v[42:45]
	v_mfma_f32_16x16x32_bf16 v[34:37], v[146:149], v[186:189], v[34:37]
	v_mfma_f32_16x16x32_bf16 v[38:41], v[154:157], v[186:189], v[38:41]
	v_mfma_f32_16x16x32_bf16 v[18:21], v[150:153], v[166:169], v[18:21]
	v_mfma_f32_16x16x32_bf16 v[10:13], v[158:161], v[166:169], v[10:13]
	v_mfma_f32_16x16x32_bf16 v[2:5], v[150:153], v[174:177], v[2:5]
	v_mfma_f32_16x16x32_bf16 v[6:9], v[158:161], v[174:177], v[6:9]
	v_mfma_f32_16x16x32_bf16 v[50:53], v[150:153], v[182:185], v[50:53]
	v_mfma_f32_16x16x32_bf16 v[42:45], v[158:161], v[182:185], v[42:45]
	v_mfma_f32_16x16x32_bf16 v[34:37], v[150:153], v[190:193], v[34:37]
	v_mfma_f32_16x16x32_bf16 v[38:41], v[158:161], v[190:193], v[38:41]
	s_barrier
	s_setprio 0
	ds_read_b128 v[162:165], v225 offset:16384
	ds_read_b128 v[166:169], v225 offset:17408
	ds_read_b128 v[170:173], v225 offset:18432
	ds_read_b128 v[174:177], v225 offset:19456
	ds_read_b128 v[178:181], v225 offset:20480
	ds_read_b128 v[182:185], v225 offset:21504
	ds_read_b128 v[186:189], v225 offset:22528
	ds_read_b128 v[190:193], v225 offset:23552
	s_add_i32 s44, s44, s49
	v_lshl_add_u64 v[206:207], s[42:43], 0, v[196:197]
	s_mov_b32 m0, s44
	s_nop 0
	global_load_lds_dwordx4 v[206:207], off
	s_add_i32 m0, s44, 0x2000
	v_lshl_add_u64 v[208:209], s[42:43], 0, v[200:201]
	s_add_u32 s42, s42, s50
	s_addc_u32 s43, s43, 0
	s_add_i32 s44, s45, s49
	global_load_lds_dwordx4 v[208:209], off
	v_lshl_add_u64 v[220:221], s[42:43], 0, v[196:197]
	s_mov_b32 m0, s44
	v_lshl_add_u64 v[226:227], s[42:43], 0, v[200:201]
	global_load_lds_dwordx4 v[220:221], off
	s_add_i32 m0, s44, 0x2000
	v_lshl_add_u64 v[228:229], s[22:23], 0, v[194:195]
	global_load_lds_dwordx4 v[226:227], off
	s_mov_b32 m0, s52
	v_lshl_add_u64 v[230:231], s[22:23], 0, v[198:199]
	global_load_lds_dwordx4 v[228:229], off
	s_mov_b32 m0, s53
	s_nop 0
	global_load_lds_dwordx4 v[230:231], off
	s_waitcnt vmcnt(8)
	s_waitcnt lgkmcnt(0)
	s_setprio 1
	s_barrier
	v_mfma_f32_16x16x32_bf16 v[90:93], v[30:33], v[162:165], v[90:93]
	v_mfma_f32_16x16x32_bf16 v[86:89], v[138:141], v[162:165], v[86:89]
	v_mfma_f32_16x16x32_bf16 v[130:133], v[30:33], v[170:173], v[130:133]
	v_mfma_f32_16x16x32_bf16 v[78:81], v[138:141], v[170:173], v[78:81]
	v_mfma_f32_16x16x32_bf16 v[126:129], v[30:33], v[178:181], v[126:129]
	v_mfma_f32_16x16x32_bf16 v[118:121], v[138:141], v[178:181], v[118:121]
	v_mfma_f32_16x16x32_bf16 v[110:113], v[138:141], v[186:189], v[110:113]
	v_mfma_f32_16x16x32_bf16 v[90:93], v[134:137], v[166:169], v[90:93]
	v_mfma_f32_16x16x32_bf16 v[86:89], v[142:145], v[166:169], v[86:89]
	v_mfma_f32_16x16x32_bf16 v[130:133], v[134:137], v[174:177], v[130:133]
	v_mfma_f32_16x16x32_bf16 v[78:81], v[142:145], v[174:177], v[78:81]
	v_mfma_f32_16x16x32_bf16 v[126:129], v[134:137], v[182:185], v[126:129]
	v_mfma_f32_16x16x32_bf16 v[118:121], v[142:145], v[182:185], v[118:121]
	v_mfma_f32_16x16x32_bf16 v[30:33], v[30:33], v[186:189], v[122:125]
	v_mfma_f32_16x16x32_bf16 v[110:113], v[142:145], v[190:193], v[110:113]
	v_mfma_f32_16x16x32_bf16 v[30:33], v[134:137], v[190:193], v[30:33]
	s_setprio 0
	s_setprio 1
	v_mfma_f32_16x16x32_bf16 v[82:85], v[146:149], v[162:165], v[82:85]
	v_mfma_f32_16x16x32_bf16 v[74:77], v[154:157], v[162:165], v[74:77]
	v_mfma_f32_16x16x32_bf16 v[66:69], v[146:149], v[170:173], v[66:69]
	v_mfma_f32_16x16x32_bf16 v[70:73], v[154:157], v[170:173], v[70:73]
	v_mfma_f32_16x16x32_bf16 v[114:117], v[146:149], v[178:181], v[114:117]
	v_mfma_f32_16x16x32_bf16 v[106:109], v[154:157], v[178:181], v[106:109]
	v_mfma_f32_16x16x32_bf16 v[98:101], v[146:149], v[186:189], v[98:101]
	v_mfma_f32_16x16x32_bf16 v[102:105], v[154:157], v[186:189], v[102:105]
	v_mfma_f32_16x16x32_bf16 v[82:85], v[150:153], v[166:169], v[82:85]
	v_mfma_f32_16x16x32_bf16 v[74:77], v[158:161], v[166:169], v[74:77]
	v_mfma_f32_16x16x32_bf16 v[66:69], v[150:153], v[174:177], v[66:69]
	v_mfma_f32_16x16x32_bf16 v[70:73], v[158:161], v[174:177], v[70:73]
	v_mfma_f32_16x16x32_bf16 v[114:117], v[150:153], v[182:185], v[114:117]
	v_mfma_f32_16x16x32_bf16 v[106:109], v[158:161], v[182:185], v[106:109]
	v_mfma_f32_16x16x32_bf16 v[98:101], v[150:153], v[190:193], v[98:101]
	v_mfma_f32_16x16x32_bf16 v[102:105], v[158:161], v[190:193], v[102:105]
	s_barrier
	s_setprio 0
	s_add_i32 s42, 0, 0x18000
	v_add_u32_e32 v0, s42, v224
	s_add_i32 s43, 0, 0x1c000
	ds_read_b128 v[122:125], v0
	ds_read_b128 v[134:137], v0 offset:1024
	ds_read_b128 v[138:141], v0 offset:2048
	ds_read_b128 v[142:145], v0 offset:3072
	v_add_u32_e32 v0, s43, v224
	ds_read_b128 v[146:149], v0
	ds_read_b128 v[150:153], v0 offset:1024
	ds_read_b128 v[154:157], v0 offset:2048
	ds_read_b128 v[158:161], v0 offset:3072
	ds_read_b128 v[162:165], v225 offset:32768
	ds_read_b128 v[166:169], v225 offset:33792
	ds_read_b128 v[170:173], v225 offset:34816
	ds_read_b128 v[174:177], v225 offset:35840
	ds_read_b128 v[178:181], v225 offset:36864
	ds_read_b128 v[182:185], v225 offset:37888
	ds_read_b128 v[186:189], v225 offset:38912
	ds_read_b128 v[190:193], v225 offset:39936
	s_add_u32 s22, s22, 0x80000
	s_addc_u32 s23, s23, 0
	s_mov_b32 m0, s54
	v_lshl_add_u64 v[232:233], s[22:23], 0, v[194:195]
	global_load_lds_dwordx4 v[232:233], off
	v_lshl_add_u64 v[232:233], s[22:23], 0, v[198:199]
	s_mov_b32 m0, s55
	s_nop 0
	global_load_lds_dwordx4 v[232:233], off
	s_waitcnt vmcnt(8)
	s_waitcnt lgkmcnt(0)
	s_setprio 1
	s_barrier
	v_mfma_f32_16x16x32_bf16 v[26:29], v[122:125], v[162:165], v[26:29]
	v_mfma_f32_16x16x32_bf16 v[22:25], v[138:141], v[162:165], v[22:25]
	v_mfma_f32_16x16x32_bf16 v[62:65], v[122:125], v[170:173], v[62:65]
	v_mfma_f32_16x16x32_bf16 v[14:17], v[138:141], v[170:173], v[14:17]
	v_mfma_f32_16x16x32_bf16 v[58:61], v[122:125], v[178:181], v[58:61]
	v_mfma_f32_16x16x32_bf16 v[54:57], v[138:141], v[178:181], v[54:57]
	v_mfma_f32_16x16x32_bf16 v[94:97], v[122:125], v[186:189], v[94:97]
	v_mfma_f32_16x16x32_bf16 v[46:49], v[138:141], v[186:189], v[46:49]
	v_mfma_f32_16x16x32_bf16 v[26:29], v[134:137], v[166:169], v[26:29]
	v_mfma_f32_16x16x32_bf16 v[22:25], v[142:145], v[166:169], v[22:25]
	v_mfma_f32_16x16x32_bf16 v[62:65], v[134:137], v[174:177], v[62:65]
	v_mfma_f32_16x16x32_bf16 v[14:17], v[142:145], v[174:177], v[14:17]
	v_mfma_f32_16x16x32_bf16 v[58:61], v[134:137], v[182:185], v[58:61]
	v_mfma_f32_16x16x32_bf16 v[54:57], v[142:145], v[182:185], v[54:57]
	v_mfma_f32_16x16x32_bf16 v[94:97], v[134:137], v[190:193], v[94:97]
	v_mfma_f32_16x16x32_bf16 v[46:49], v[142:145], v[190:193], v[46:49]
	s_setprio 0
	s_setprio 1
	v_mfma_f32_16x16x32_bf16 v[18:21], v[146:149], v[162:165], v[18:21]
	v_mfma_f32_16x16x32_bf16 v[10:13], v[154:157], v[162:165], v[10:13]
	v_mfma_f32_16x16x32_bf16 v[2:5], v[146:149], v[170:173], v[2:5]
	v_mfma_f32_16x16x32_bf16 v[6:9], v[154:157], v[170:173], v[6:9]
	v_mfma_f32_16x16x32_bf16 v[50:53], v[146:149], v[178:181], v[50:53]
	v_mfma_f32_16x16x32_bf16 v[42:45], v[154:157], v[178:181], v[42:45]
	v_mfma_f32_16x16x32_bf16 v[34:37], v[146:149], v[186:189], v[34:37]
	v_mfma_f32_16x16x32_bf16 v[38:41], v[154:157], v[186:189], v[38:41]
	v_mfma_f32_16x16x32_bf16 v[18:21], v[150:153], v[166:169], v[18:21]
	v_mfma_f32_16x16x32_bf16 v[10:13], v[158:161], v[166:169], v[10:13]
	v_mfma_f32_16x16x32_bf16 v[2:5], v[150:153], v[174:177], v[2:5]
	v_mfma_f32_16x16x32_bf16 v[6:9], v[158:161], v[174:177], v[6:9]
	v_mfma_f32_16x16x32_bf16 v[50:53], v[150:153], v[182:185], v[50:53]
	v_mfma_f32_16x16x32_bf16 v[42:45], v[158:161], v[182:185], v[42:45]
	v_mfma_f32_16x16x32_bf16 v[34:37], v[150:153], v[190:193], v[34:37]
	v_mfma_f32_16x16x32_bf16 v[38:41], v[158:161], v[190:193], v[38:41]
	s_barrier
	s_setprio 0
	ds_read_b128 v[162:165], v225 offset:49152
	ds_read_b128 v[166:169], v225 offset:50176
	ds_read_b128 v[170:173], v225 offset:51200
	ds_read_b128 v[174:177], v225 offset:52224
	ds_read_b128 v[178:181], v225 offset:53248
	ds_read_b128 v[182:185], v225 offset:54272
	ds_read_b128 v[186:189], v225 offset:55296
	ds_read_b128 v[190:193], v225 offset:56320
	s_add_i32 s22, s42, s49
	v_lshl_add_u64 v[206:207], v[206:207], 0, s[2:3]
	s_mov_b32 m0, s22
	s_nop 0
	global_load_lds_dwordx4 v[206:207], off
	v_lshl_add_u64 v[206:207], v[208:209], 0, s[2:3]
	s_add_i32 m0, s22, 0x2000
	s_add_i32 s22, s43, s49
	global_load_lds_dwordx4 v[206:207], off
	v_lshl_add_u64 v[206:207], v[220:221], 0, s[2:3]
	s_mov_b32 m0, s22
	s_nop 0
	global_load_lds_dwordx4 v[206:207], off
	v_lshl_add_u64 v[206:207], v[226:227], 0, s[2:3]
	s_add_i32 m0, s22, 0x2000
	s_nop 0
	global_load_lds_dwordx4 v[206:207], off
	v_lshl_add_u64 v[206:207], v[228:229], 0, s[2:3]
	s_mov_b32 m0, s61
	s_nop 0
	global_load_lds_dwordx4 v[206:207], off
	v_lshl_add_u64 v[206:207], v[230:231], 0, s[2:3]
	s_mov_b32 m0, s62
	s_nop 0
	global_load_lds_dwordx4 v[206:207], off
	s_waitcnt vmcnt(8)
	s_waitcnt lgkmcnt(0)
	s_setprio 1
	s_barrier
	v_mfma_f32_16x16x32_bf16 v[30:33], v[122:125], v[186:189], v[30:33]
	v_mfma_f32_16x16x32_bf16 v[90:93], v[122:125], v[162:165], v[90:93]
	v_mfma_f32_16x16x32_bf16 v[86:89], v[138:141], v[162:165], v[86:89]
	v_mfma_f32_16x16x32_bf16 v[130:133], v[122:125], v[170:173], v[130:133]
	v_mfma_f32_16x16x32_bf16 v[78:81], v[138:141], v[170:173], v[78:81]
	v_mfma_f32_16x16x32_bf16 v[126:129], v[122:125], v[178:181], v[126:129]
	v_mfma_f32_16x16x32_bf16 v[118:121], v[138:141], v[178:181], v[118:121]
	v_mfma_f32_16x16x32_bf16 v[122:125], v[134:137], v[190:193], v[30:33]
	v_mfma_f32_16x16x32_bf16 v[30:33], v[138:141], v[186:189], v[110:113]
	v_mfma_f32_16x16x32_bf16 v[90:93], v[134:137], v[166:169], v[90:93]
	v_mfma_f32_16x16x32_bf16 v[86:89], v[142:145], v[166:169], v[86:89]
	v_mfma_f32_16x16x32_bf16 v[130:133], v[134:137], v[174:177], v[130:133]
	v_mfma_f32_16x16x32_bf16 v[78:81], v[142:145], v[174:177], v[78:81]
	v_mfma_f32_16x16x32_bf16 v[126:129], v[134:137], v[182:185], v[126:129]
	v_mfma_f32_16x16x32_bf16 v[118:121], v[142:145], v[182:185], v[118:121]
	v_mfma_f32_16x16x32_bf16 v[110:113], v[142:145], v[190:193], v[30:33]
	s_setprio 0
	s_setprio 1
	v_mfma_f32_16x16x32_bf16 v[30:33], v[146:149], v[162:165], v[82:85]
	v_mfma_f32_16x16x32_bf16 v[82:85], v[150:153], v[166:169], v[30:33]
	v_mfma_f32_16x16x32_bf16 v[30:33], v[154:157], v[162:165], v[74:77]
	v_mfma_f32_16x16x32_bf16 v[74:77], v[158:161], v[166:169], v[30:33]
	v_mfma_f32_16x16x32_bf16 v[30:33], v[146:149], v[170:173], v[66:69]
	v_mfma_f32_16x16x32_bf16 v[66:69], v[150:153], v[174:177], v[30:33]
	v_mfma_f32_16x16x32_bf16 v[30:33], v[154:157], v[170:173], v[70:73]
	v_mfma_f32_16x16x32_bf16 v[70:73], v[158:161], v[174:177], v[30:33]
	v_mfma_f32_16x16x32_bf16 v[30:33], v[146:149], v[178:181], v[114:117]
	v_mfma_f32_16x16x32_bf16 v[114:117], v[150:153], v[182:185], v[30:33]
	v_mfma_f32_16x16x32_bf16 v[30:33], v[154:157], v[178:181], v[106:109]
	v_mfma_f32_16x16x32_bf16 v[106:109], v[158:161], v[182:185], v[30:33]
	v_mfma_f32_16x16x32_bf16 v[30:33], v[146:149], v[186:189], v[98:101]
	v_mfma_f32_16x16x32_bf16 v[98:101], v[150:153], v[190:193], v[30:33]
	v_mfma_f32_16x16x32_bf16 v[30:33], v[154:157], v[186:189], v[102:105]
	v_mfma_f32_16x16x32_bf16 v[102:105], v[158:161], v[190:193], v[30:33]
	s_barrier
	s_setprio 0
	s_add_u32 s38, s38, 0x100
	s_addc_u32 s39, s39, 0
	s_add_u32 s15, s15, 0x100
	s_addc_u32 s21, s21, 0
	s_cmp_ge_u32 s41, s56
	s_mov_b32 s22, s41
	s_cbranch_scc0 .LBB0_883

.LBB0_990:
	s_add_i32 s48, 0, 0x10000
	s_add_i32 s17, 0, 0x14000
	v_add_u32_e32 v156, s48, v140
	v_add_u32_e32 v172, s17, v140
	ds_read_b128 v[144:147], v156
	ds_read_b128 v[148:151], v156 offset:1024
	ds_read_b128 v[152:155], v156 offset:2048
	ds_read_b128 v[156:159], v156 offset:3072
	ds_read_b128 v[160:163], v172
	ds_read_b128 v[164:167], v172 offset:1024
	ds_read_b128 v[168:171], v172 offset:2048
	ds_read_b128 v[172:175], v172 offset:3072
	ds_read_b128 v[176:179], v143
	ds_read_b128 v[180:183], v143 offset:1024
	ds_read_b128 v[184:187], v143 offset:2048
	ds_read_b128 v[188:191], v143 offset:3072
	ds_read_b128 v[192:195], v143 offset:4096
	ds_read_b128 v[196:199], v143 offset:5120
	ds_read_b128 v[200:203], v143 offset:6144
	ds_read_b128 v[204:207], v143 offset:7168
	s_add_u32 s17, s36, 0xfff80080
	s_addc_u32 s22, s37, -1
	s_cmp_eq_u32 s15, 4
	s_cselect_b32 s39, s19, s22
	s_cselect_b32 s38, s18, s17
	s_cselect_b32 s23, s21, s13
	s_cselect_b32 s22, s20, s5
	v_lshl_add_u64 v[208:209], s[36:37], 0, v[136:137]
	s_add_i32 m0, s7, 0xc000
	s_nop 0
	global_load_lds_dwordx4 v[208:209], off
	v_lshl_add_u64 v[208:209], s[36:37], 0, v[138:139]
	s_add_i32 m0, s7, 0xe000
	s_nop 0
	global_load_lds_dwordx4 v[208:209], off
	s_waitcnt vmcnt(8)
	s_waitcnt lgkmcnt(0)
	s_setprio 1
	s_barrier
	v_mfma_f32_16x16x32_bf16 v[126:129], v[144:147], v[176:179], v[126:129]
	v_mfma_f32_16x16x32_bf16 v[122:125], v[152:155], v[176:179], v[122:125]
	v_mfma_f32_16x16x32_bf16 v[118:121], v[144:147], v[184:187], v[118:121]
	v_mfma_f32_16x16x32_bf16 v[114:117], v[152:155], v[184:187], v[114:117]
	v_mfma_f32_16x16x32_bf16 v[102:105], v[144:147], v[192:195], v[102:105]
	v_mfma_f32_16x16x32_bf16 v[98:101], v[152:155], v[192:195], v[98:101]
	v_mfma_f32_16x16x32_bf16 v[86:89], v[144:147], v[200:203], v[86:89]
	v_mfma_f32_16x16x32_bf16 v[82:85], v[152:155], v[200:203], v[82:85]
	v_mfma_f32_16x16x32_bf16 v[126:129], v[148:151], v[180:183], v[126:129]
	v_mfma_f32_16x16x32_bf16 v[122:125], v[156:159], v[180:183], v[122:125]
	v_mfma_f32_16x16x32_bf16 v[118:121], v[148:151], v[188:191], v[118:121]
	v_mfma_f32_16x16x32_bf16 v[114:117], v[156:159], v[188:191], v[114:117]
	v_mfma_f32_16x16x32_bf16 v[102:105], v[148:151], v[196:199], v[102:105]
	v_mfma_f32_16x16x32_bf16 v[98:101], v[156:159], v[196:199], v[98:101]
	v_mfma_f32_16x16x32_bf16 v[86:89], v[148:151], v[204:207], v[86:89]
	v_mfma_f32_16x16x32_bf16 v[82:85], v[156:159], v[204:207], v[82:85]
	s_setprio 0
	s_setprio 1
	v_mfma_f32_16x16x32_bf16 v[110:113], v[160:163], v[176:179], v[110:113]
	v_mfma_f32_16x16x32_bf16 v[106:109], v[168:171], v[176:179], v[106:109]
	v_mfma_f32_16x16x32_bf16 v[94:97], v[160:163], v[184:187], v[94:97]
	v_mfma_f32_16x16x32_bf16 v[90:93], v[168:171], v[184:187], v[90:93]
	v_mfma_f32_16x16x32_bf16 v[78:81], v[160:163], v[192:195], v[78:81]
	v_mfma_f32_16x16x32_bf16 v[74:77], v[168:171], v[192:195], v[74:77]
	v_mfma_f32_16x16x32_bf16 v[70:73], v[160:163], v[200:203], v[70:73]
	v_mfma_f32_16x16x32_bf16 v[66:69], v[168:171], v[200:203], v[66:69]
	v_mfma_f32_16x16x32_bf16 v[110:113], v[164:167], v[180:183], v[110:113]
	v_mfma_f32_16x16x32_bf16 v[106:109], v[172:175], v[180:183], v[106:109]
	v_mfma_f32_16x16x32_bf16 v[94:97], v[164:167], v[188:191], v[94:97]
	v_mfma_f32_16x16x32_bf16 v[90:93], v[172:175], v[188:191], v[90:93]
	v_mfma_f32_16x16x32_bf16 v[78:81], v[164:167], v[196:199], v[78:81]
	v_mfma_f32_16x16x32_bf16 v[74:77], v[172:175], v[196:199], v[74:77]
	v_mfma_f32_16x16x32_bf16 v[70:73], v[164:167], v[204:207], v[70:73]
	v_mfma_f32_16x16x32_bf16 v[66:69], v[172:175], v[204:207], v[66:69]
	s_barrier
	s_setprio 0
	ds_read_b128 v[176:179], v143 offset:16384
	ds_read_b128 v[180:183], v143 offset:17408
	ds_read_b128 v[184:187], v143 offset:18432
	ds_read_b128 v[188:191], v143 offset:19456
	ds_read_b128 v[192:195], v143 offset:20480
	ds_read_b128 v[196:199], v143 offset:21504
	ds_read_b128 v[200:203], v143 offset:22528
	ds_read_b128 v[204:207], v143 offset:23552
	s_add_i32 s48, s48, s40
	v_lshl_add_u64 v[208:209], s[22:23], 0, v[0:1]
	s_mov_b32 m0, s48
	s_nop 0
	global_load_lds_dwordx4 v[208:209], off
	s_add_i32 m0, s48, 0x2000
	s_add_u32 s48, s22, 0x80000
	v_lshl_add_u64 v[216:217], s[22:23], 0, v[130:131]
	s_addc_u32 s49, s23, 0
	s_add_i32 s17, s17, s40
	global_load_lds_dwordx4 v[216:217], off
	v_lshl_add_u64 v[220:221], s[48:49], 0, v[0:1]
	s_mov_b32 m0, s17
	v_lshl_add_u64 v[222:223], s[38:39], 0, v[132:133]
	global_load_lds_dwordx4 v[220:221], off
	v_lshl_add_u64 v[220:221], s[48:49], 0, v[130:131]
	s_add_i32 m0, s17, 0x2000
	s_nop 0
	global_load_lds_dwordx4 v[220:221], off
	v_lshl_add_u64 v[220:221], s[38:39], 0, v[134:135]
	s_mov_b32 m0, s7
	s_nop 0
	global_load_lds_dwordx4 v[220:221], off
	s_mov_b32 m0, s9
	s_nop 0
	global_load_lds_dwordx4 v[222:223], off
	s_waitcnt vmcnt(8)
	s_waitcnt lgkmcnt(0)
	s_setprio 1
	s_barrier
	v_mfma_f32_16x16x32_bf16 v[62:65], v[144:147], v[176:179], v[62:65]
	v_mfma_f32_16x16x32_bf16 v[58:61], v[152:155], v[176:179], v[58:61]
	v_mfma_f32_16x16x32_bf16 v[54:57], v[144:147], v[184:187], v[54:57]
	v_mfma_f32_16x16x32_bf16 v[50:53], v[152:155], v[184:187], v[50:53]
	v_mfma_f32_16x16x32_bf16 v[38:41], v[144:147], v[192:195], v[38:41]
	v_mfma_f32_16x16x32_bf16 v[34:37], v[152:155], v[192:195], v[34:37]
	v_mfma_f32_16x16x32_bf16 v[22:25], v[144:147], v[200:203], v[22:25]
	v_mfma_f32_16x16x32_bf16 v[18:21], v[152:155], v[200:203], v[18:21]
	v_mfma_f32_16x16x32_bf16 v[62:65], v[148:151], v[180:183], v[62:65]
	v_mfma_f32_16x16x32_bf16 v[58:61], v[156:159], v[180:183], v[58:61]
	v_mfma_f32_16x16x32_bf16 v[54:57], v[148:151], v[188:191], v[54:57]
	v_mfma_f32_16x16x32_bf16 v[50:53], v[156:159], v[188:191], v[50:53]
	v_mfma_f32_16x16x32_bf16 v[38:41], v[148:151], v[196:199], v[38:41]
	v_mfma_f32_16x16x32_bf16 v[34:37], v[156:159], v[196:199], v[34:37]
	v_mfma_f32_16x16x32_bf16 v[22:25], v[148:151], v[204:207], v[22:25]
	v_mfma_f32_16x16x32_bf16 v[18:21], v[156:159], v[204:207], v[18:21]
	s_setprio 0
	s_setprio 1
	v_mfma_f32_16x16x32_bf16 v[46:49], v[160:163], v[176:179], v[46:49]
	v_mfma_f32_16x16x32_bf16 v[42:45], v[168:171], v[176:179], v[42:45]
	v_mfma_f32_16x16x32_bf16 v[30:33], v[160:163], v[184:187], v[30:33]
	v_mfma_f32_16x16x32_bf16 v[26:29], v[168:171], v[184:187], v[26:29]
	v_mfma_f32_16x16x32_bf16 v[14:17], v[160:163], v[192:195], v[14:17]
	v_mfma_f32_16x16x32_bf16 v[10:13], v[168:171], v[192:195], v[10:13]
	v_mfma_f32_16x16x32_bf16 v[6:9], v[160:163], v[200:203], v[6:9]
	v_mfma_f32_16x16x32_bf16 v[2:5], v[168:171], v[200:203], v[2:5]
	v_mfma_f32_16x16x32_bf16 v[46:49], v[164:167], v[180:183], v[46:49]
	v_mfma_f32_16x16x32_bf16 v[42:45], v[172:175], v[180:183], v[42:45]
	v_mfma_f32_16x16x32_bf16 v[30:33], v[164:167], v[188:191], v[30:33]
	v_mfma_f32_16x16x32_bf16 v[26:29], v[172:175], v[188:191], v[26:29]
	v_mfma_f32_16x16x32_bf16 v[14:17], v[164:167], v[196:199], v[14:17]
	v_mfma_f32_16x16x32_bf16 v[10:13], v[172:175], v[196:199], v[10:13]
	v_mfma_f32_16x16x32_bf16 v[6:9], v[164:167], v[204:207], v[6:9]
	v_mfma_f32_16x16x32_bf16 v[2:5], v[172:175], v[204:207], v[2:5]
	s_barrier
	s_setprio 0
	s_add_i32 s17, 0, 0x18000
	s_add_i32 s48, 0, 0x1c000
	v_add_u32_e32 v156, s17, v140
	v_add_u32_e32 v172, s48, v140
	ds_read_b128 v[144:147], v156
	ds_read_b128 v[148:151], v156 offset:1024
	ds_read_b128 v[152:155], v156 offset:2048
	ds_read_b128 v[156:159], v156 offset:3072
	ds_read_b128 v[160:163], v172
	ds_read_b128 v[164:167], v172 offset:1024
	ds_read_b128 v[168:171], v172 offset:2048
	ds_read_b128 v[172:175], v172 offset:3072
	ds_read_b128 v[176:179], v143 offset:32768
	ds_read_b128 v[180:183], v143 offset:33792
	ds_read_b128 v[184:187], v143 offset:34816
	ds_read_b128 v[188:191], v143 offset:35840
	ds_read_b128 v[192:195], v143 offset:36864
	ds_read_b128 v[196:199], v143 offset:37888
	ds_read_b128 v[200:203], v143 offset:38912
	ds_read_b128 v[204:207], v143 offset:39936
	s_add_u32 s38, s38, 0x80000
	s_addc_u32 s39, s39, 0
	s_mov_b32 m0, s42
	v_lshl_add_u64 v[224:225], s[38:39], 0, v[134:135]
	global_load_lds_dwordx4 v[224:225], off
	v_lshl_add_u64 v[224:225], s[38:39], 0, v[132:133]
	s_mov_b32 m0, s43
	s_nop 0
	global_load_lds_dwordx4 v[224:225], off
	s_waitcnt vmcnt(8)
	s_waitcnt lgkmcnt(0)
	s_setprio 1
	s_barrier
	v_mfma_f32_16x16x32_bf16 v[126:129], v[144:147], v[176:179], v[126:129]
	v_mfma_f32_16x16x32_bf16 v[122:125], v[152:155], v[176:179], v[122:125]
	v_mfma_f32_16x16x32_bf16 v[118:121], v[144:147], v[184:187], v[118:121]
	v_mfma_f32_16x16x32_bf16 v[114:117], v[152:155], v[184:187], v[114:117]
	v_mfma_f32_16x16x32_bf16 v[102:105], v[144:147], v[192:195], v[102:105]
	v_mfma_f32_16x16x32_bf16 v[98:101], v[152:155], v[192:195], v[98:101]
	v_mfma_f32_16x16x32_bf16 v[86:89], v[144:147], v[200:203], v[86:89]
	v_mfma_f32_16x16x32_bf16 v[82:85], v[152:155], v[200:203], v[82:85]
	v_mfma_f32_16x16x32_bf16 v[126:129], v[148:151], v[180:183], v[126:129]
	v_mfma_f32_16x16x32_bf16 v[122:125], v[156:159], v[180:183], v[122:125]
	v_mfma_f32_16x16x32_bf16 v[118:121], v[148:151], v[188:191], v[118:121]
	v_mfma_f32_16x16x32_bf16 v[114:117], v[156:159], v[188:191], v[114:117]
	v_mfma_f32_16x16x32_bf16 v[102:105], v[148:151], v[196:199], v[102:105]
	v_mfma_f32_16x16x32_bf16 v[98:101], v[156:159], v[196:199], v[98:101]
	v_mfma_f32_16x16x32_bf16 v[86:89], v[148:151], v[204:207], v[86:89]
	v_mfma_f32_16x16x32_bf16 v[82:85], v[156:159], v[204:207], v[82:85]
	s_setprio 0
	s_setprio 1
	v_mfma_f32_16x16x32_bf16 v[110:113], v[160:163], v[176:179], v[110:113]
	v_mfma_f32_16x16x32_bf16 v[106:109], v[168:171], v[176:179], v[106:109]
	v_mfma_f32_16x16x32_bf16 v[94:97], v[160:163], v[184:187], v[94:97]
	v_mfma_f32_16x16x32_bf16 v[90:93], v[168:171], v[184:187], v[90:93]
	v_mfma_f32_16x16x32_bf16 v[78:81], v[160:163], v[192:195], v[78:81]
	v_mfma_f32_16x16x32_bf16 v[74:77], v[168:171], v[192:195], v[74:77]
	v_mfma_f32_16x16x32_bf16 v[70:73], v[160:163], v[200:203], v[70:73]
	v_mfma_f32_16x16x32_bf16 v[66:69], v[168:171], v[200:203], v[66:69]
	v_mfma_f32_16x16x32_bf16 v[110:113], v[164:167], v[180:183], v[110:113]
	v_mfma_f32_16x16x32_bf16 v[106:109], v[172:175], v[180:183], v[106:109]
	v_mfma_f32_16x16x32_bf16 v[94:97], v[164:167], v[188:191], v[94:97]
	v_mfma_f32_16x16x32_bf16 v[90:93], v[172:175], v[188:191], v[90:93]
	v_mfma_f32_16x16x32_bf16 v[78:81], v[164:167], v[196:199], v[78:81]
	v_mfma_f32_16x16x32_bf16 v[74:77], v[172:175], v[196:199], v[74:77]
	v_mfma_f32_16x16x32_bf16 v[70:73], v[164:167], v[204:207], v[70:73]
	v_mfma_f32_16x16x32_bf16 v[66:69], v[172:175], v[204:207], v[66:69]
	s_barrier
	s_setprio 0
	ds_read_b128 v[176:179], v143 offset:49152
	ds_read_b128 v[180:183], v143 offset:50176
	ds_read_b128 v[184:187], v143 offset:51200
	ds_read_b128 v[188:191], v143 offset:52224
	ds_read_b128 v[192:195], v143 offset:53248
	ds_read_b128 v[196:199], v143 offset:54272
	ds_read_b128 v[200:203], v143 offset:55296
	ds_read_b128 v[204:207], v143 offset:56320
	s_add_i32 s17, s17, s40
	v_lshl_add_u64 v[208:209], v[208:209], 0, s[2:3]
	s_mov_b32 m0, s17
	s_nop 0
	global_load_lds_dwordx4 v[208:209], off
	s_add_i32 m0, s17, 0x2000
	s_add_u32 s22, s22, 0x80080
	v_lshl_add_u64 v[208:209], v[216:217], 0, s[2:3]
	s_addc_u32 s23, s23, 0
	s_add_i32 s17, s48, s40
	global_load_lds_dwordx4 v[208:209], off
	v_lshl_add_u64 v[208:209], s[22:23], 0, v[0:1]
	s_mov_b32 m0, s17
	s_nop 0
	global_load_lds_dwordx4 v[208:209], off
	v_lshl_add_u64 v[208:209], s[22:23], 0, v[130:131]
	s_add_i32 m0, s17, 0x2000
	s_nop 0
	global_load_lds_dwordx4 v[208:209], off
	v_lshl_add_u64 v[208:209], v[220:221], 0, s[2:3]
	s_mov_b32 m0, s44
	s_nop 0
	global_load_lds_dwordx4 v[208:209], off
	v_lshl_add_u64 v[208:209], v[222:223], 0, s[2:3]
	s_mov_b32 m0, s45
	s_nop 0
	global_load_lds_dwordx4 v[208:209], off
	s_waitcnt vmcnt(8)
	s_waitcnt lgkmcnt(0)
	s_setprio 1
	s_barrier
	v_mfma_f32_16x16x32_bf16 v[62:65], v[144:147], v[176:179], v[62:65]
	v_mfma_f32_16x16x32_bf16 v[58:61], v[152:155], v[176:179], v[58:61]
	v_mfma_f32_16x16x32_bf16 v[54:57], v[144:147], v[184:187], v[54:57]
	v_mfma_f32_16x16x32_bf16 v[50:53], v[152:155], v[184:187], v[50:53]
	v_mfma_f32_16x16x32_bf16 v[38:41], v[144:147], v[192:195], v[38:41]
	v_mfma_f32_16x16x32_bf16 v[34:37], v[152:155], v[192:195], v[34:37]
	v_mfma_f32_16x16x32_bf16 v[22:25], v[144:147], v[200:203], v[22:25]
	v_mfma_f32_16x16x32_bf16 v[18:21], v[152:155], v[200:203], v[18:21]
	v_mfma_f32_16x16x32_bf16 v[62:65], v[148:151], v[180:183], v[62:65]
	v_mfma_f32_16x16x32_bf16 v[58:61], v[156:159], v[180:183], v[58:61]
	v_mfma_f32_16x16x32_bf16 v[54:57], v[148:151], v[188:191], v[54:57]
	v_mfma_f32_16x16x32_bf16 v[50:53], v[156:159], v[188:191], v[50:53]
	v_mfma_f32_16x16x32_bf16 v[38:41], v[148:151], v[196:199], v[38:41]
	v_mfma_f32_16x16x32_bf16 v[34:37], v[156:159], v[196:199], v[34:37]
	v_mfma_f32_16x16x32_bf16 v[22:25], v[148:151], v[204:207], v[22:25]
	v_mfma_f32_16x16x32_bf16 v[18:21], v[156:159], v[204:207], v[18:21]
	s_setprio 0
	s_setprio 1
	v_mfma_f32_16x16x32_bf16 v[46:49], v[160:163], v[176:179], v[46:49]
	v_mfma_f32_16x16x32_bf16 v[42:45], v[168:171], v[176:179], v[42:45]
	v_mfma_f32_16x16x32_bf16 v[30:33], v[160:163], v[184:187], v[30:33]
	v_mfma_f32_16x16x32_bf16 v[26:29], v[168:171], v[184:187], v[26:29]
	v_mfma_f32_16x16x32_bf16 v[14:17], v[160:163], v[192:195], v[14:17]
	v_mfma_f32_16x16x32_bf16 v[10:13], v[168:171], v[192:195], v[10:13]
	v_mfma_f32_16x16x32_bf16 v[6:9], v[160:163], v[200:203], v[6:9]
	v_mfma_f32_16x16x32_bf16 v[2:5], v[168:171], v[200:203], v[2:5]
	v_mfma_f32_16x16x32_bf16 v[46:49], v[164:167], v[180:183], v[46:49]
	v_mfma_f32_16x16x32_bf16 v[42:45], v[172:175], v[180:183], v[42:45]
	v_mfma_f32_16x16x32_bf16 v[30:33], v[164:167], v[188:191], v[30:33]
	v_mfma_f32_16x16x32_bf16 v[26:29], v[172:175], v[188:191], v[26:29]
	v_mfma_f32_16x16x32_bf16 v[14:17], v[164:167], v[196:199], v[14:17]
	v_mfma_f32_16x16x32_bf16 v[10:13], v[172:175], v[196:199], v[10:13]
	v_mfma_f32_16x16x32_bf16 v[6:9], v[164:167], v[204:207], v[6:9]
	v_mfma_f32_16x16x32_bf16 v[2:5], v[172:175], v[204:207], v[2:5]
	s_barrier
	s_setprio 0
	s_add_i32 s15, s15, 2
	s_add_u32 s36, s36, 0x100
	s_addc_u32 s37, s37, 0
	s_add_u32 s5, s5, 0x100
	s_addc_u32 s13, s13, 0
	s_cmp_gt_u32 s15, 5
	s_cbranch_scc0 .LBB0_990

.LBB0_1201:
	s_add_i32 s47, 0, 0x10000
	s_add_i32 s50, 0, 0x14000
	v_add_u32_e32 v142, s47, v171
	v_add_u32_e32 v168, s50, v171
	ds_read_b128 v[130:133], v142
	ds_read_b128 v[134:137], v142 offset:1024
	ds_read_b128 v[138:141], v142 offset:2048
	ds_read_b128 v[142:145], v142 offset:3072
	ds_read_b128 v[156:159], v168
	ds_read_b128 v[160:163], v168 offset:1024
	ds_read_b128 v[164:167], v168 offset:2048
	ds_read_b128 v[174:177], v168 offset:3072
	ds_read_b128 v[178:181], v173
	ds_read_b128 v[182:185], v173 offset:1024
	ds_read_b128 v[186:189], v173 offset:2048
	ds_read_b128 v[190:193], v173 offset:3072
	ds_read_b128 v[194:197], v173 offset:4096
	ds_read_b128 v[198:201], v173 offset:5120
	ds_read_b128 v[202:205], v173 offset:6144
	ds_read_b128 v[206:209], v173 offset:7168
	s_add_u32 s20, s18, 0xfff80080
	s_addc_u32 s21, s19, -1
	s_cmp_eq_u32 s37, 4
	s_cselect_b32 s23, s11, s21
	s_cselect_b32 s22, s10, s20
	s_cselect_b32 s21, s7, s36
	s_cselect_b32 s20, s9, s15
	v_lshl_add_u64 v[168:169], s[18:19], 0, v[152:153]
	s_add_i32 m0, s17, 0xc000
	s_nop 0
	global_load_lds_dwordx4 v[168:169], off
	v_lshl_add_u64 v[168:169], s[18:19], 0, v[154:155]
	s_add_i32 m0, s17, 0xe000
	s_nop 0
	global_load_lds_dwordx4 v[168:169], off
	s_waitcnt vmcnt(8)
	s_waitcnt lgkmcnt(0)
	s_setprio 1
	s_barrier
	v_mfma_f32_16x16x32_bf16 v[126:129], v[130:133], v[178:181], v[126:129]
	v_mfma_f32_16x16x32_bf16 v[122:125], v[138:141], v[178:181], v[122:125]
	v_mfma_f32_16x16x32_bf16 v[118:121], v[130:133], v[186:189], v[118:121]
	v_mfma_f32_16x16x32_bf16 v[106:109], v[138:141], v[186:189], v[106:109]
	v_mfma_f32_16x16x32_bf16 v[98:101], v[130:133], v[194:197], v[98:101]
	v_mfma_f32_16x16x32_bf16 v[90:93], v[138:141], v[194:197], v[90:93]
	v_mfma_f32_16x16x32_bf16 v[82:85], v[130:133], v[202:205], v[82:85]
	v_mfma_f32_16x16x32_bf16 v[74:77], v[138:141], v[202:205], v[74:77]
	v_mfma_f32_16x16x32_bf16 v[126:129], v[134:137], v[182:185], v[126:129]
	v_mfma_f32_16x16x32_bf16 v[122:125], v[142:145], v[182:185], v[122:125]
	v_mfma_f32_16x16x32_bf16 v[118:121], v[134:137], v[190:193], v[118:121]
	v_mfma_f32_16x16x32_bf16 v[106:109], v[142:145], v[190:193], v[106:109]
	v_mfma_f32_16x16x32_bf16 v[98:101], v[134:137], v[198:201], v[98:101]
	v_mfma_f32_16x16x32_bf16 v[90:93], v[142:145], v[198:201], v[90:93]
	v_mfma_f32_16x16x32_bf16 v[82:85], v[134:137], v[206:209], v[82:85]
	v_mfma_f32_16x16x32_bf16 v[74:77], v[142:145], v[206:209], v[74:77]
	s_setprio 0
	s_setprio 1
	v_mfma_f32_16x16x32_bf16 v[114:117], v[156:159], v[178:181], v[114:117]
	v_mfma_f32_16x16x32_bf16 v[110:113], v[164:167], v[178:181], v[110:113]
	v_mfma_f32_16x16x32_bf16 v[102:105], v[156:159], v[186:189], v[102:105]
	v_mfma_f32_16x16x32_bf16 v[94:97], v[164:167], v[186:189], v[94:97]
	v_mfma_f32_16x16x32_bf16 v[86:89], v[156:159], v[194:197], v[86:89]
	v_mfma_f32_16x16x32_bf16 v[78:81], v[164:167], v[194:197], v[78:81]
	v_mfma_f32_16x16x32_bf16 v[70:73], v[156:159], v[202:205], v[70:73]
	v_mfma_f32_16x16x32_bf16 v[66:69], v[164:167], v[202:205], v[66:69]
	v_mfma_f32_16x16x32_bf16 v[114:117], v[160:163], v[182:185], v[114:117]
	v_mfma_f32_16x16x32_bf16 v[110:113], v[174:177], v[182:185], v[110:113]
	v_mfma_f32_16x16x32_bf16 v[102:105], v[160:163], v[190:193], v[102:105]
	v_mfma_f32_16x16x32_bf16 v[94:97], v[174:177], v[190:193], v[94:97]
	v_mfma_f32_16x16x32_bf16 v[86:89], v[160:163], v[198:201], v[86:89]
	v_mfma_f32_16x16x32_bf16 v[78:81], v[174:177], v[198:201], v[78:81]
	v_mfma_f32_16x16x32_bf16 v[70:73], v[160:163], v[206:209], v[70:73]
	v_mfma_f32_16x16x32_bf16 v[66:69], v[174:177], v[206:209], v[66:69]
	s_barrier
	s_setprio 0
	ds_read_b128 v[178:181], v173 offset:16384
	ds_read_b128 v[182:185], v173 offset:17408
	ds_read_b128 v[186:189], v173 offset:18432
	ds_read_b128 v[190:193], v173 offset:19456
	ds_read_b128 v[194:197], v173 offset:20480
	ds_read_b128 v[198:201], v173 offset:21504
	ds_read_b128 v[202:205], v173 offset:22528
	ds_read_b128 v[206:209], v173 offset:23552
	s_add_i32 s47, s47, s38
	v_lshl_add_u64 v[168:169], s[20:21], 0, v[0:1]
	s_mov_b32 m0, s47
	s_nop 0
	global_load_lds_dwordx4 v[168:169], off
	s_add_i32 m0, s47, 0x2000
	s_add_u32 s48, s20, 0x20000
	v_lshl_add_u64 v[216:217], s[20:21], 0, v[146:147]
	s_addc_u32 s49, s21, 0
	s_add_i32 s47, s50, s38
	global_load_lds_dwordx4 v[216:217], off
	v_lshl_add_u64 v[220:221], s[48:49], 0, v[0:1]
	s_mov_b32 m0, s47
	v_lshl_add_u64 v[222:223], s[22:23], 0, v[148:149]
	global_load_lds_dwordx4 v[220:221], off
	v_lshl_add_u64 v[220:221], s[48:49], 0, v[146:147]
	s_add_i32 m0, s47, 0x2000
	s_nop 0
	global_load_lds_dwordx4 v[220:221], off
	v_lshl_add_u64 v[220:221], s[22:23], 0, v[150:151]
	s_mov_b32 m0, s17
	s_nop 0
	global_load_lds_dwordx4 v[220:221], off
	s_mov_b32 m0, s40
	s_nop 0
	global_load_lds_dwordx4 v[222:223], off
	s_waitcnt vmcnt(8)
	s_waitcnt lgkmcnt(0)
	s_setprio 1
	s_barrier
	v_mfma_f32_16x16x32_bf16 v[62:65], v[130:133], v[178:181], v[62:65]
	v_mfma_f32_16x16x32_bf16 v[58:61], v[138:141], v[178:181], v[58:61]
	v_mfma_f32_16x16x32_bf16 v[50:53], v[130:133], v[186:189], v[50:53]
	v_mfma_f32_16x16x32_bf16 v[42:45], v[138:141], v[186:189], v[42:45]
	v_mfma_f32_16x16x32_bf16 v[34:37], v[130:133], v[194:197], v[34:37]
	v_mfma_f32_16x16x32_bf16 v[26:29], v[138:141], v[194:197], v[26:29]
	v_mfma_f32_16x16x32_bf16 v[18:21], v[130:133], v[202:205], v[18:21]
	v_mfma_f32_16x16x32_bf16 v[10:13], v[138:141], v[202:205], v[10:13]
	v_mfma_f32_16x16x32_bf16 v[62:65], v[134:137], v[182:185], v[62:65]
	v_mfma_f32_16x16x32_bf16 v[58:61], v[142:145], v[182:185], v[58:61]
	v_mfma_f32_16x16x32_bf16 v[50:53], v[134:137], v[190:193], v[50:53]
	v_mfma_f32_16x16x32_bf16 v[42:45], v[142:145], v[190:193], v[42:45]
	v_mfma_f32_16x16x32_bf16 v[34:37], v[134:137], v[198:201], v[34:37]
	v_mfma_f32_16x16x32_bf16 v[26:29], v[142:145], v[198:201], v[26:29]
	v_mfma_f32_16x16x32_bf16 v[18:21], v[134:137], v[206:209], v[18:21]
	v_mfma_f32_16x16x32_bf16 v[10:13], v[142:145], v[206:209], v[10:13]
	s_setprio 0
	s_setprio 1
	v_mfma_f32_16x16x32_bf16 v[54:57], v[156:159], v[178:181], v[54:57]
	v_mfma_f32_16x16x32_bf16 v[46:49], v[164:167], v[178:181], v[46:49]
	v_mfma_f32_16x16x32_bf16 v[38:41], v[156:159], v[186:189], v[38:41]
	v_mfma_f32_16x16x32_bf16 v[30:33], v[164:167], v[186:189], v[30:33]
	v_mfma_f32_16x16x32_bf16 v[22:25], v[156:159], v[194:197], v[22:25]
	v_mfma_f32_16x16x32_bf16 v[14:17], v[164:167], v[194:197], v[14:17]
	v_mfma_f32_16x16x32_bf16 v[6:9], v[156:159], v[202:205], v[6:9]
	v_mfma_f32_16x16x32_bf16 v[2:5], v[164:167], v[202:205], v[2:5]
	v_mfma_f32_16x16x32_bf16 v[54:57], v[160:163], v[182:185], v[54:57]
	v_mfma_f32_16x16x32_bf16 v[46:49], v[174:177], v[182:185], v[46:49]
	v_mfma_f32_16x16x32_bf16 v[38:41], v[160:163], v[190:193], v[38:41]
	v_mfma_f32_16x16x32_bf16 v[30:33], v[174:177], v[190:193], v[30:33]
	v_mfma_f32_16x16x32_bf16 v[22:25], v[160:163], v[198:201], v[22:25]
	v_mfma_f32_16x16x32_bf16 v[14:17], v[174:177], v[198:201], v[14:17]
	v_mfma_f32_16x16x32_bf16 v[6:9], v[160:163], v[206:209], v[6:9]
	v_mfma_f32_16x16x32_bf16 v[2:5], v[174:177], v[206:209], v[2:5]
	s_barrier
	s_setprio 0
	s_add_i32 s47, 0, 0x18000
	s_add_i32 s48, 0, 0x1c000
	v_add_u32_e32 v142, s47, v171
	v_add_u32_e32 v174, s48, v171
	ds_read_b128 v[130:133], v142
	ds_read_b128 v[134:137], v142 offset:1024
	ds_read_b128 v[138:141], v142 offset:2048
	ds_read_b128 v[142:145], v142 offset:3072
	ds_read_b128 v[156:159], v174
	ds_read_b128 v[160:163], v174 offset:1024
	ds_read_b128 v[164:167], v174 offset:2048
	ds_read_b128 v[174:177], v174 offset:3072
	ds_read_b128 v[178:181], v173 offset:32768
	ds_read_b128 v[182:185], v173 offset:33792
	ds_read_b128 v[186:189], v173 offset:34816
	ds_read_b128 v[190:193], v173 offset:35840
	ds_read_b128 v[194:197], v173 offset:36864
	ds_read_b128 v[198:201], v173 offset:37888
	ds_read_b128 v[202:205], v173 offset:38912
	ds_read_b128 v[206:209], v173 offset:39936
	s_add_u32 s22, s22, 0x80000
	s_addc_u32 s23, s23, 0
	s_mov_b32 m0, s41
	v_lshl_add_u64 v[224:225], s[22:23], 0, v[150:151]
	global_load_lds_dwordx4 v[224:225], off
	v_lshl_add_u64 v[224:225], s[22:23], 0, v[148:149]
	s_mov_b32 m0, s42
	s_nop 0
	global_load_lds_dwordx4 v[224:225], off
	s_waitcnt vmcnt(8)
	s_waitcnt lgkmcnt(0)
	s_setprio 1
	s_barrier
	v_mfma_f32_16x16x32_bf16 v[126:129], v[130:133], v[178:181], v[126:129]
	v_mfma_f32_16x16x32_bf16 v[122:125], v[138:141], v[178:181], v[122:125]
	v_mfma_f32_16x16x32_bf16 v[118:121], v[130:133], v[186:189], v[118:121]
	v_mfma_f32_16x16x32_bf16 v[106:109], v[138:141], v[186:189], v[106:109]
	v_mfma_f32_16x16x32_bf16 v[98:101], v[130:133], v[194:197], v[98:101]
	v_mfma_f32_16x16x32_bf16 v[90:93], v[138:141], v[194:197], v[90:93]
	v_mfma_f32_16x16x32_bf16 v[82:85], v[130:133], v[202:205], v[82:85]
	v_mfma_f32_16x16x32_bf16 v[74:77], v[138:141], v[202:205], v[74:77]
	v_mfma_f32_16x16x32_bf16 v[126:129], v[134:137], v[182:185], v[126:129]
	v_mfma_f32_16x16x32_bf16 v[122:125], v[142:145], v[182:185], v[122:125]
	v_mfma_f32_16x16x32_bf16 v[118:121], v[134:137], v[190:193], v[118:121]
	v_mfma_f32_16x16x32_bf16 v[106:109], v[142:145], v[190:193], v[106:109]
	v_mfma_f32_16x16x32_bf16 v[98:101], v[134:137], v[198:201], v[98:101]
	v_mfma_f32_16x16x32_bf16 v[90:93], v[142:145], v[198:201], v[90:93]
	v_mfma_f32_16x16x32_bf16 v[82:85], v[134:137], v[206:209], v[82:85]
	v_mfma_f32_16x16x32_bf16 v[74:77], v[142:145], v[206:209], v[74:77]
	s_setprio 0
	s_setprio 1
	v_mfma_f32_16x16x32_bf16 v[114:117], v[156:159], v[178:181], v[114:117]
	v_mfma_f32_16x16x32_bf16 v[110:113], v[164:167], v[178:181], v[110:113]
	v_mfma_f32_16x16x32_bf16 v[102:105], v[156:159], v[186:189], v[102:105]
	v_mfma_f32_16x16x32_bf16 v[94:97], v[164:167], v[186:189], v[94:97]
	v_mfma_f32_16x16x32_bf16 v[86:89], v[156:159], v[194:197], v[86:89]
	v_mfma_f32_16x16x32_bf16 v[78:81], v[164:167], v[194:197], v[78:81]
	v_mfma_f32_16x16x32_bf16 v[70:73], v[156:159], v[202:205], v[70:73]
	v_mfma_f32_16x16x32_bf16 v[66:69], v[164:167], v[202:205], v[66:69]
	v_mfma_f32_16x16x32_bf16 v[114:117], v[160:163], v[182:185], v[114:117]
	v_mfma_f32_16x16x32_bf16 v[110:113], v[174:177], v[182:185], v[110:113]
	v_mfma_f32_16x16x32_bf16 v[102:105], v[160:163], v[190:193], v[102:105]
	v_mfma_f32_16x16x32_bf16 v[94:97], v[174:177], v[190:193], v[94:97]
	v_mfma_f32_16x16x32_bf16 v[86:89], v[160:163], v[198:201], v[86:89]
	v_mfma_f32_16x16x32_bf16 v[78:81], v[174:177], v[198:201], v[78:81]
	v_mfma_f32_16x16x32_bf16 v[70:73], v[160:163], v[206:209], v[70:73]
	v_mfma_f32_16x16x32_bf16 v[66:69], v[174:177], v[206:209], v[66:69]
	s_barrier
	s_setprio 0
	ds_read_b128 v[178:181], v173 offset:49152
	ds_read_b128 v[182:185], v173 offset:50176
	ds_read_b128 v[186:189], v173 offset:51200
	ds_read_b128 v[190:193], v173 offset:52224
	ds_read_b128 v[194:197], v173 offset:53248
	ds_read_b128 v[198:201], v173 offset:54272
	ds_read_b128 v[202:205], v173 offset:55296
	ds_read_b128 v[206:209], v173 offset:56320
	s_add_i32 s22, s47, s38
	v_lshl_add_u64 v[168:169], v[168:169], 0, s[2:3]
	s_mov_b32 m0, s22
	s_nop 0
	global_load_lds_dwordx4 v[168:169], off
	s_add_i32 m0, s22, 0x2000
	s_add_u32 s20, s20, 0x20080
	v_lshl_add_u64 v[168:169], v[216:217], 0, s[2:3]
	s_addc_u32 s21, s21, 0
	s_add_i32 s22, s48, s38
	global_load_lds_dwordx4 v[168:169], off
	v_lshl_add_u64 v[168:169], s[20:21], 0, v[0:1]
	s_mov_b32 m0, s22
	s_nop 0
	global_load_lds_dwordx4 v[168:169], off
	v_lshl_add_u64 v[168:169], s[20:21], 0, v[146:147]
	s_add_i32 m0, s22, 0x2000
	s_nop 0
	global_load_lds_dwordx4 v[168:169], off
	v_lshl_add_u64 v[168:169], v[220:221], 0, s[2:3]
	s_mov_b32 m0, s43
	s_nop 0
	global_load_lds_dwordx4 v[168:169], off
	v_lshl_add_u64 v[168:169], v[222:223], 0, s[2:3]
	s_mov_b32 m0, s44
	s_nop 0
	global_load_lds_dwordx4 v[168:169], off
	s_waitcnt vmcnt(8)
	s_waitcnt lgkmcnt(0)
	s_setprio 1
	s_barrier
	v_mfma_f32_16x16x32_bf16 v[62:65], v[130:133], v[178:181], v[62:65]
	v_mfma_f32_16x16x32_bf16 v[58:61], v[138:141], v[178:181], v[58:61]
	v_mfma_f32_16x16x32_bf16 v[50:53], v[130:133], v[186:189], v[50:53]
	v_mfma_f32_16x16x32_bf16 v[42:45], v[138:141], v[186:189], v[42:45]
	v_mfma_f32_16x16x32_bf16 v[34:37], v[130:133], v[194:197], v[34:37]
	v_mfma_f32_16x16x32_bf16 v[26:29], v[138:141], v[194:197], v[26:29]
	v_mfma_f32_16x16x32_bf16 v[18:21], v[130:133], v[202:205], v[18:21]
	v_mfma_f32_16x16x32_bf16 v[10:13], v[138:141], v[202:205], v[10:13]
	v_mfma_f32_16x16x32_bf16 v[62:65], v[134:137], v[182:185], v[62:65]
	v_mfma_f32_16x16x32_bf16 v[58:61], v[142:145], v[182:185], v[58:61]
	v_mfma_f32_16x16x32_bf16 v[50:53], v[134:137], v[190:193], v[50:53]
	v_mfma_f32_16x16x32_bf16 v[42:45], v[142:145], v[190:193], v[42:45]
	v_mfma_f32_16x16x32_bf16 v[34:37], v[134:137], v[198:201], v[34:37]
	v_mfma_f32_16x16x32_bf16 v[26:29], v[142:145], v[198:201], v[26:29]
	v_mfma_f32_16x16x32_bf16 v[18:21], v[134:137], v[206:209], v[18:21]
	v_mfma_f32_16x16x32_bf16 v[10:13], v[142:145], v[206:209], v[10:13]
	s_setprio 0
	s_setprio 1
	v_mfma_f32_16x16x32_bf16 v[54:57], v[156:159], v[178:181], v[54:57]
	v_mfma_f32_16x16x32_bf16 v[46:49], v[164:167], v[178:181], v[46:49]
	v_mfma_f32_16x16x32_bf16 v[38:41], v[156:159], v[186:189], v[38:41]
	v_mfma_f32_16x16x32_bf16 v[30:33], v[164:167], v[186:189], v[30:33]
	v_mfma_f32_16x16x32_bf16 v[22:25], v[156:159], v[194:197], v[22:25]
	v_mfma_f32_16x16x32_bf16 v[14:17], v[164:167], v[194:197], v[14:17]
	v_mfma_f32_16x16x32_bf16 v[6:9], v[156:159], v[202:205], v[6:9]
	v_mfma_f32_16x16x32_bf16 v[2:5], v[164:167], v[202:205], v[2:5]
	v_mfma_f32_16x16x32_bf16 v[54:57], v[160:163], v[182:185], v[54:57]
	v_mfma_f32_16x16x32_bf16 v[46:49], v[174:177], v[182:185], v[46:49]
	v_mfma_f32_16x16x32_bf16 v[38:41], v[160:163], v[190:193], v[38:41]
	v_mfma_f32_16x16x32_bf16 v[30:33], v[174:177], v[190:193], v[30:33]
	v_mfma_f32_16x16x32_bf16 v[22:25], v[160:163], v[198:201], v[22:25]
	v_mfma_f32_16x16x32_bf16 v[14:17], v[174:177], v[198:201], v[14:17]
	v_mfma_f32_16x16x32_bf16 v[6:9], v[160:163], v[206:209], v[6:9]
	v_mfma_f32_16x16x32_bf16 v[2:5], v[174:177], v[206:209], v[2:5]
	s_barrier
	s_setprio 0
	s_add_i32 s37, s37, 2
	s_add_u32 s18, s18, 0x100
	s_addc_u32 s19, s19, 0
	s_add_u32 s15, s15, 0x100
	s_addc_u32 s36, s36, 0
	s_cmp_gt_u32 s37, 5
	s_cbranch_scc0 .LBB0_1201

.LBB0_1565:
	s_add_i32 s54, 0, 0x10000
	s_add_i32 s56, 0, 0x14000
	v_add_u32_e32 v158, 0x10000, v160
	ds_read_b128 v[164:167], v158
	ds_read_b128 v[168:171], v158 offset:1024
	ds_read_b128 v[172:175], v158 offset:2048
	ds_read_b128 v[176:179], v158 offset:3072
	ds_read_b128 v[180:183], v158 offset:16384
	ds_read_b128 v[184:187], v158 offset:17408
	ds_read_b128 v[188:191], v158 offset:18432
	ds_read_b128 v[192:195], v158 offset:19456
	ds_read_b128 v[196:199], v162
	ds_read_b128 v[200:203], v162 offset:1024
	ds_read_b128 v[204:207], v162 offset:2048
	ds_read_b128 v[220:223], v162 offset:3072
	ds_read_b128 v[224:227], v162 offset:4096
	ds_read_b128 v[228:231], v162 offset:5120
	ds_read_b128 v[232:235], v162 offset:6144
	ds_read_b128 v[236:239], v162 offset:7168
	s_add_u32 s20, s18, 0xfff80080
	s_addc_u32 s21, s19, -1
	s_cmp_eq_u32 s53, 28
	s_cselect_b32 s23, s9, s21
	s_cselect_b32 s22, s15, s20
	s_cselect_b32 s21, s7, s52
	s_cselect_b32 s20, s50, s51
	s_add_i32 m0, s17, 0xc000
	s_nop 0
	global_load_lds_dwordx4 v154, s[18:19]
	s_add_i32 m0, s17, 0xe000
	s_nop 0
	global_load_lds_dwordx4 v156, s[18:19]
	s_waitcnt vmcnt(8)
	s_waitcnt lgkmcnt(0)
	s_setprio 1
	s_barrier
	v_mfma_f32_16x16x32_bf16 v[122:125], v[164:167], v[196:199], v[122:125]
	v_mfma_f32_16x16x32_bf16 v[114:117], v[172:175], v[196:199], v[114:117]
	v_mfma_f32_16x16x32_bf16 v[106:109], v[164:167], v[204:207], v[106:109]
	v_mfma_f32_16x16x32_bf16 v[98:101], v[172:175], v[204:207], v[98:101]
	v_mfma_f32_16x16x32_bf16 v[90:93], v[164:167], v[224:227], v[90:93]
	v_mfma_f32_16x16x32_bf16 v[82:85], v[172:175], v[224:227], v[82:85]
	v_mfma_f32_16x16x32_bf16 v[74:77], v[164:167], v[232:235], v[74:77]
	v_mfma_f32_16x16x32_bf16 v[66:69], v[172:175], v[232:235], v[66:69]
	v_mfma_f32_16x16x32_bf16 v[122:125], v[168:171], v[200:203], v[122:125]
	v_mfma_f32_16x16x32_bf16 v[114:117], v[176:179], v[200:203], v[114:117]
	v_mfma_f32_16x16x32_bf16 v[106:109], v[168:171], v[220:223], v[106:109]
	v_mfma_f32_16x16x32_bf16 v[98:101], v[176:179], v[220:223], v[98:101]
	v_mfma_f32_16x16x32_bf16 v[90:93], v[168:171], v[228:231], v[90:93]
	v_mfma_f32_16x16x32_bf16 v[82:85], v[176:179], v[228:231], v[82:85]
	v_mfma_f32_16x16x32_bf16 v[74:77], v[168:171], v[236:239], v[74:77]
	v_mfma_f32_16x16x32_bf16 v[66:69], v[176:179], v[236:239], v[66:69]
	s_setprio 0
	s_setprio 1
	v_mfma_f32_16x16x32_bf16 v[126:129], v[180:183], v[196:199], v[126:129]
	v_mfma_f32_16x16x32_bf16 v[118:121], v[188:191], v[196:199], v[118:121]
	v_mfma_f32_16x16x32_bf16 v[110:113], v[180:183], v[204:207], v[110:113]
	v_mfma_f32_16x16x32_bf16 v[102:105], v[188:191], v[204:207], v[102:105]
	v_mfma_f32_16x16x32_bf16 v[94:97], v[180:183], v[224:227], v[94:97]
	v_mfma_f32_16x16x32_bf16 v[86:89], v[188:191], v[224:227], v[86:89]
	v_mfma_f32_16x16x32_bf16 v[78:81], v[180:183], v[232:235], v[78:81]
	v_mfma_f32_16x16x32_bf16 v[70:73], v[188:191], v[232:235], v[70:73]
	v_mfma_f32_16x16x32_bf16 v[126:129], v[184:187], v[200:203], v[126:129]
	v_mfma_f32_16x16x32_bf16 v[118:121], v[192:195], v[200:203], v[118:121]
	v_mfma_f32_16x16x32_bf16 v[110:113], v[184:187], v[220:223], v[110:113]
	v_mfma_f32_16x16x32_bf16 v[102:105], v[192:195], v[220:223], v[102:105]
	v_mfma_f32_16x16x32_bf16 v[94:97], v[184:187], v[228:231], v[94:97]
	v_mfma_f32_16x16x32_bf16 v[86:89], v[192:195], v[228:231], v[86:89]
	v_mfma_f32_16x16x32_bf16 v[78:81], v[184:187], v[236:239], v[78:81]
	v_mfma_f32_16x16x32_bf16 v[70:73], v[192:195], v[236:239], v[70:73]
	s_barrier
	s_setprio 0
	ds_read_b128 v[196:199], v162 offset:16384
	ds_read_b128 v[200:203], v162 offset:17408
	ds_read_b128 v[204:207], v162 offset:18432
	ds_read_b128 v[220:223], v162 offset:19456
	ds_read_b128 v[224:227], v162 offset:20480
	ds_read_b128 v[228:231], v162 offset:21504
	ds_read_b128 v[232:235], v162 offset:22528
	ds_read_b128 v[236:239], v162 offset:23552
	s_add_i32 s54, s54, s41
	s_mov_b32 m0, s54
	s_nop 0
	global_load_lds_dwordx4 v0, s[20:21]
	s_add_i32 m0, s54, 0x2000
	s_add_u32 s54, s20, 0x80000
	s_addc_u32 s55, s21, 0
	s_add_i32 s56, s56, s41
	global_load_lds_dwordx4 v130, s[20:21]
	s_mov_b32 m0, s56
	s_nop 0
	global_load_lds_dwordx4 v0, s[54:55]
	s_add_i32 m0, s56, 0x2000
	s_nop 0
	global_load_lds_dwordx4 v130, s[54:55]
	s_mov_b32 m0, s17
	s_nop 0
	global_load_lds_dwordx4 v134, s[22:23]
	s_mov_b32 m0, s43
	s_nop 0
	global_load_lds_dwordx4 v132, s[22:23]
	s_waitcnt vmcnt(8)
	s_waitcnt lgkmcnt(0)
	s_setprio 1
	s_barrier
	v_mfma_f32_16x16x32_bf16 v[58:61], v[164:167], v[196:199], v[58:61]
	v_mfma_f32_16x16x32_bf16 v[50:53], v[172:175], v[196:199], v[50:53]
	v_mfma_f32_16x16x32_bf16 v[42:45], v[164:167], v[204:207], v[42:45]
	v_mfma_f32_16x16x32_bf16 v[34:37], v[172:175], v[204:207], v[34:37]
	v_mfma_f32_16x16x32_bf16 v[26:29], v[164:167], v[224:227], v[26:29]
	v_mfma_f32_16x16x32_bf16 v[18:21], v[172:175], v[224:227], v[18:21]
	v_mfma_f32_16x16x32_bf16 v[10:13], v[164:167], v[232:235], v[10:13]
	v_mfma_f32_16x16x32_bf16 v[2:5], v[172:175], v[232:235], v[2:5]
	v_mfma_f32_16x16x32_bf16 v[58:61], v[168:171], v[200:203], v[58:61]
	v_mfma_f32_16x16x32_bf16 v[50:53], v[176:179], v[200:203], v[50:53]
	v_mfma_f32_16x16x32_bf16 v[42:45], v[168:171], v[220:223], v[42:45]
	v_mfma_f32_16x16x32_bf16 v[34:37], v[176:179], v[220:223], v[34:37]
	v_mfma_f32_16x16x32_bf16 v[26:29], v[168:171], v[228:231], v[26:29]
	v_mfma_f32_16x16x32_bf16 v[18:21], v[176:179], v[228:231], v[18:21]
	v_mfma_f32_16x16x32_bf16 v[10:13], v[168:171], v[236:239], v[10:13]
	v_mfma_f32_16x16x32_bf16 v[2:5], v[176:179], v[236:239], v[2:5]
	s_setprio 0
	s_setprio 1
	v_mfma_f32_16x16x32_bf16 v[62:65], v[180:183], v[196:199], v[62:65]
	v_mfma_f32_16x16x32_bf16 v[54:57], v[188:191], v[196:199], v[54:57]
	v_mfma_f32_16x16x32_bf16 v[46:49], v[180:183], v[204:207], v[46:49]
	v_mfma_f32_16x16x32_bf16 v[38:41], v[188:191], v[204:207], v[38:41]
	v_mfma_f32_16x16x32_bf16 v[30:33], v[180:183], v[224:227], v[30:33]
	v_mfma_f32_16x16x32_bf16 v[22:25], v[188:191], v[224:227], v[22:25]
	v_mfma_f32_16x16x32_bf16 v[14:17], v[180:183], v[232:235], v[14:17]
	v_mfma_f32_16x16x32_bf16 v[6:9], v[188:191], v[232:235], v[6:9]
	v_mfma_f32_16x16x32_bf16 v[62:65], v[184:187], v[200:203], v[62:65]
	v_mfma_f32_16x16x32_bf16 v[54:57], v[192:195], v[200:203], v[54:57]
	v_mfma_f32_16x16x32_bf16 v[46:49], v[184:187], v[220:223], v[46:49]
	v_mfma_f32_16x16x32_bf16 v[38:41], v[192:195], v[220:223], v[38:41]
	v_mfma_f32_16x16x32_bf16 v[30:33], v[184:187], v[228:231], v[30:33]
	v_mfma_f32_16x16x32_bf16 v[22:25], v[192:195], v[228:231], v[22:25]
	v_mfma_f32_16x16x32_bf16 v[14:17], v[184:187], v[236:239], v[14:17]
	v_mfma_f32_16x16x32_bf16 v[6:9], v[192:195], v[236:239], v[6:9]
	s_barrier
	s_setprio 0
	ds_read_b128 v[164:167], v158 offset:32768
	ds_read_b128 v[168:171], v158 offset:33792
	ds_read_b128 v[172:175], v158 offset:34816
	ds_read_b128 v[176:179], v158 offset:35840
	ds_read_b128 v[180:183], v158 offset:49152
	ds_read_b128 v[184:187], v158 offset:50176
	ds_read_b128 v[188:191], v158 offset:51200
	ds_read_b128 v[192:195], v158 offset:52224
	s_add_i32 s54, 0, 0x18000
	s_add_i32 s55, 0, 0x1c000
	ds_read_b128 v[196:199], v162 offset:32768
	ds_read_b128 v[200:203], v162 offset:33792
	ds_read_b128 v[204:207], v162 offset:34816
	ds_read_b128 v[220:223], v162 offset:35840
	ds_read_b128 v[224:227], v162 offset:36864
	ds_read_b128 v[228:231], v162 offset:37888
	ds_read_b128 v[232:235], v162 offset:38912
	ds_read_b128 v[236:239], v162 offset:39936
	s_add_u32 s22, s22, 0x80000
	s_addc_u32 s23, s23, 0
	s_mov_b32 m0, s44
	s_nop 0
	global_load_lds_dwordx4 v134, s[22:23]
	s_mov_b32 m0, s45
	s_nop 0
	global_load_lds_dwordx4 v132, s[22:23]
	s_waitcnt vmcnt(8)
	s_waitcnt lgkmcnt(0)
	s_setprio 1
	s_barrier
	v_mfma_f32_16x16x32_bf16 v[122:125], v[164:167], v[196:199], v[122:125]
	v_mfma_f32_16x16x32_bf16 v[114:117], v[172:175], v[196:199], v[114:117]
	v_mfma_f32_16x16x32_bf16 v[106:109], v[164:167], v[204:207], v[106:109]
	v_mfma_f32_16x16x32_bf16 v[98:101], v[172:175], v[204:207], v[98:101]
	v_mfma_f32_16x16x32_bf16 v[90:93], v[164:167], v[224:227], v[90:93]
	v_mfma_f32_16x16x32_bf16 v[82:85], v[172:175], v[224:227], v[82:85]
	v_mfma_f32_16x16x32_bf16 v[74:77], v[164:167], v[232:235], v[74:77]
	v_mfma_f32_16x16x32_bf16 v[66:69], v[172:175], v[232:235], v[66:69]
	v_mfma_f32_16x16x32_bf16 v[122:125], v[168:171], v[200:203], v[122:125]
	v_mfma_f32_16x16x32_bf16 v[114:117], v[176:179], v[200:203], v[114:117]
	v_mfma_f32_16x16x32_bf16 v[106:109], v[168:171], v[220:223], v[106:109]
	v_mfma_f32_16x16x32_bf16 v[98:101], v[176:179], v[220:223], v[98:101]
	v_mfma_f32_16x16x32_bf16 v[90:93], v[168:171], v[228:231], v[90:93]
	v_mfma_f32_16x16x32_bf16 v[82:85], v[176:179], v[228:231], v[82:85]
	v_mfma_f32_16x16x32_bf16 v[74:77], v[168:171], v[236:239], v[74:77]
	v_mfma_f32_16x16x32_bf16 v[66:69], v[176:179], v[236:239], v[66:69]
	s_setprio 0
	s_setprio 1
	v_mfma_f32_16x16x32_bf16 v[126:129], v[180:183], v[196:199], v[126:129]
	v_mfma_f32_16x16x32_bf16 v[118:121], v[188:191], v[196:199], v[118:121]
	v_mfma_f32_16x16x32_bf16 v[110:113], v[180:183], v[204:207], v[110:113]
	v_mfma_f32_16x16x32_bf16 v[102:105], v[188:191], v[204:207], v[102:105]
	v_mfma_f32_16x16x32_bf16 v[94:97], v[180:183], v[224:227], v[94:97]
	v_mfma_f32_16x16x32_bf16 v[86:89], v[188:191], v[224:227], v[86:89]
	v_mfma_f32_16x16x32_bf16 v[78:81], v[180:183], v[232:235], v[78:81]
	v_mfma_f32_16x16x32_bf16 v[70:73], v[188:191], v[232:235], v[70:73]
	v_mfma_f32_16x16x32_bf16 v[126:129], v[184:187], v[200:203], v[126:129]
	v_mfma_f32_16x16x32_bf16 v[118:121], v[192:195], v[200:203], v[118:121]
	v_mfma_f32_16x16x32_bf16 v[110:113], v[184:187], v[220:223], v[110:113]
	v_mfma_f32_16x16x32_bf16 v[102:105], v[192:195], v[220:223], v[102:105]
	v_mfma_f32_16x16x32_bf16 v[94:97], v[184:187], v[228:231], v[94:97]
	v_mfma_f32_16x16x32_bf16 v[86:89], v[192:195], v[228:231], v[86:89]
	v_mfma_f32_16x16x32_bf16 v[78:81], v[184:187], v[236:239], v[78:81]
	v_mfma_f32_16x16x32_bf16 v[70:73], v[192:195], v[236:239], v[70:73]
	s_barrier
	s_setprio 0
	ds_read_b128 v[196:199], v162 offset:49152
	ds_read_b128 v[200:203], v162 offset:50176
	ds_read_b128 v[204:207], v162 offset:51200
	ds_read_b128 v[220:223], v162 offset:52224
	ds_read_b128 v[224:227], v162 offset:53248
	ds_read_b128 v[228:231], v162 offset:54272
	ds_read_b128 v[232:235], v162 offset:55296
	ds_read_b128 v[236:239], v162 offset:56320
	s_add_u32 vcc_lo, s22, 0xfff80080
	s_addc_u32 vcc_hi, s23, -1
	s_add_i32 s22, s54, s41
	s_add_i32 s56, s55, s41
	s_add_u32 s54, s20, 0x80
	s_addc_u32 s55, s21, 0
	s_add_u32 s20, s20, 0x80080
	s_addc_u32 s21, s21, 0
	s_mov_b32 m0, s22
	s_nop 0
	global_load_lds_dwordx4 v0, s[54:55]
	s_add_i32 m0, s22, 0x2000
	s_nop 0
	global_load_lds_dwordx4 v130, s[54:55]
	s_mov_b32 m0, s56
	s_nop 0
	global_load_lds_dwordx4 v0, s[20:21]
	s_add_i32 m0, s56, 0x2000
	s_nop 0
	global_load_lds_dwordx4 v130, s[20:21]
	s_mov_b32 m0, s46
	s_nop 0
	global_load_lds_dwordx4 v134, vcc
	s_mov_b32 m0, s47
	s_nop 0
	global_load_lds_dwordx4 v132, vcc
	s_waitcnt vmcnt(8)
	s_waitcnt lgkmcnt(0)
	s_setprio 1
	s_barrier
	v_mfma_f32_16x16x32_bf16 v[58:61], v[164:167], v[196:199], v[58:61]
	v_mfma_f32_16x16x32_bf16 v[50:53], v[172:175], v[196:199], v[50:53]
	v_mfma_f32_16x16x32_bf16 v[42:45], v[164:167], v[204:207], v[42:45]
	v_mfma_f32_16x16x32_bf16 v[34:37], v[172:175], v[204:207], v[34:37]
	v_mfma_f32_16x16x32_bf16 v[26:29], v[164:167], v[224:227], v[26:29]
	v_mfma_f32_16x16x32_bf16 v[18:21], v[172:175], v[224:227], v[18:21]
	v_mfma_f32_16x16x32_bf16 v[10:13], v[164:167], v[232:235], v[10:13]
	v_mfma_f32_16x16x32_bf16 v[2:5], v[172:175], v[232:235], v[2:5]
	v_mfma_f32_16x16x32_bf16 v[58:61], v[168:171], v[200:203], v[58:61]
	v_mfma_f32_16x16x32_bf16 v[50:53], v[176:179], v[200:203], v[50:53]
	v_mfma_f32_16x16x32_bf16 v[42:45], v[168:171], v[220:223], v[42:45]
	v_mfma_f32_16x16x32_bf16 v[34:37], v[176:179], v[220:223], v[34:37]
	v_mfma_f32_16x16x32_bf16 v[26:29], v[168:171], v[228:231], v[26:29]
	v_mfma_f32_16x16x32_bf16 v[18:21], v[176:179], v[228:231], v[18:21]
	v_mfma_f32_16x16x32_bf16 v[10:13], v[168:171], v[236:239], v[10:13]
	v_mfma_f32_16x16x32_bf16 v[2:5], v[176:179], v[236:239], v[2:5]
	s_setprio 0
	s_setprio 1
	v_mfma_f32_16x16x32_bf16 v[62:65], v[180:183], v[196:199], v[62:65]
	v_mfma_f32_16x16x32_bf16 v[54:57], v[188:191], v[196:199], v[54:57]
	v_mfma_f32_16x16x32_bf16 v[46:49], v[180:183], v[204:207], v[46:49]
	v_mfma_f32_16x16x32_bf16 v[38:41], v[188:191], v[204:207], v[38:41]
	v_mfma_f32_16x16x32_bf16 v[30:33], v[180:183], v[224:227], v[30:33]
	v_mfma_f32_16x16x32_bf16 v[22:25], v[188:191], v[224:227], v[22:25]
	v_mfma_f32_16x16x32_bf16 v[14:17], v[180:183], v[232:235], v[14:17]
	v_mfma_f32_16x16x32_bf16 v[6:9], v[188:191], v[232:235], v[6:9]
	v_mfma_f32_16x16x32_bf16 v[62:65], v[184:187], v[200:203], v[62:65]
	v_mfma_f32_16x16x32_bf16 v[54:57], v[192:195], v[200:203], v[54:57]
	v_mfma_f32_16x16x32_bf16 v[46:49], v[184:187], v[220:223], v[46:49]
	v_mfma_f32_16x16x32_bf16 v[38:41], v[192:195], v[220:223], v[38:41]
	v_mfma_f32_16x16x32_bf16 v[30:33], v[184:187], v[228:231], v[30:33]
	v_mfma_f32_16x16x32_bf16 v[22:25], v[192:195], v[228:231], v[22:25]
	v_mfma_f32_16x16x32_bf16 v[14:17], v[184:187], v[236:239], v[14:17]
	v_mfma_f32_16x16x32_bf16 v[6:9], v[192:195], v[236:239], v[6:9]
	s_barrier
	s_setprio 0
	s_add_i32 s53, s53, 2
	s_add_u32 s18, s18, 0x100
	s_addc_u32 s19, s19, 0
	s_add_u32 s51, s51, 0x100
	s_addc_u32 s52, s52, 0
	s_cmp_gt_u32 s53, 29
	s_cbranch_scc0 .LBB0_1565

.LBB0_1844:
	s_add_i32 s38, 0, 0x10000
	v_add_u32_e32 v0, s38, v246
	s_add_i32 s40, 0, 0x14000
	ds_read_b128 v[130:133], v0
	ds_read_b128 v[134:137], v0 offset:1024
	ds_read_b128 v[138:141], v0 offset:2048
	ds_read_b128 v[142:145], v0 offset:3072
	v_add_u32_e32 v0, s40, v246
	ds_read_b128 v[146:149], v0
	ds_read_b128 v[150:153], v0 offset:1024
	ds_read_b128 v[154:157], v0 offset:2048
	ds_read_b128 v[158:161], v0 offset:3072
	ds_read_b128 v[162:165], v247
	ds_read_b128 v[166:169], v247 offset:1024
	ds_read_b128 v[170:173], v247 offset:2048
	ds_read_b128 v[174:177], v247 offset:3072
	ds_read_b128 v[178:181], v247 offset:4096
	ds_read_b128 v[182:185], v247 offset:5120
	ds_read_b128 v[186:189], v247 offset:6144
	ds_read_b128 v[190:193], v247 offset:7168
	s_add_u32 s14, s12, 0x4000
	s_addc_u32 s15, s13, 0
	s_cmpk_eq_i32 s37, 0x54
	s_cselect_b32 s18, s6, s14
	s_cselect_b32 s19, s7, s15
	s_cselect_b32 s16, s8, s11
	s_cselect_b32 s17, s9, s36
	s_add_u32 s14, s18, 0x8000
	s_addc_u32 s15, s19, 0
	v_lshl_add_u64 v[194:195], s[12:13], 0, v[228:229]
	s_add_i32 m0, s47, 0xc000
	s_nop 0
	global_load_lds_dwordx4 v[194:195], off
	v_lshl_add_u64 v[194:195], s[12:13], 0, v[230:231]
	s_add_i32 m0, s47, 0xe000
	s_nop 0
	global_load_lds_dwordx4 v[194:195], off
	s_waitcnt vmcnt(8)
	s_waitcnt lgkmcnt(0)
	s_setprio 1
	s_barrier
	v_mfma_f32_16x16x32_bf16 v[126:129], v[130:133], v[162:165], v[126:129]
	v_mfma_f32_16x16x32_bf16 v[122:125], v[138:141], v[162:165], v[122:125]
	v_mfma_f32_16x16x32_bf16 v[114:117], v[130:133], v[170:173], v[114:117]
	v_mfma_f32_16x16x32_bf16 v[106:109], v[138:141], v[170:173], v[106:109]
	v_mfma_f32_16x16x32_bf16 v[94:97], v[130:133], v[178:181], v[94:97]
	v_mfma_f32_16x16x32_bf16 v[90:93], v[138:141], v[178:181], v[90:93]
	v_mfma_f32_16x16x32_bf16 v[86:89], v[130:133], v[186:189], v[86:89]
	v_mfma_f32_16x16x32_bf16 v[82:85], v[138:141], v[186:189], v[82:85]
	v_mfma_f32_16x16x32_bf16 v[126:129], v[134:137], v[166:169], v[126:129]
	v_mfma_f32_16x16x32_bf16 v[122:125], v[142:145], v[166:169], v[122:125]
	v_mfma_f32_16x16x32_bf16 v[114:117], v[134:137], v[174:177], v[114:117]
	v_mfma_f32_16x16x32_bf16 v[106:109], v[142:145], v[174:177], v[106:109]
	v_mfma_f32_16x16x32_bf16 v[94:97], v[134:137], v[182:185], v[94:97]
	v_mfma_f32_16x16x32_bf16 v[90:93], v[142:145], v[182:185], v[90:93]
	v_mfma_f32_16x16x32_bf16 v[86:89], v[134:137], v[190:193], v[86:89]
	v_mfma_f32_16x16x32_bf16 v[82:85], v[142:145], v[190:193], v[82:85]
	s_setprio 0
	s_setprio 1
	v_mfma_f32_16x16x32_bf16 v[118:121], v[146:149], v[162:165], v[118:121]
	v_mfma_f32_16x16x32_bf16 v[110:113], v[154:157], v[162:165], v[110:113]
	v_mfma_f32_16x16x32_bf16 v[102:105], v[146:149], v[170:173], v[102:105]
	v_mfma_f32_16x16x32_bf16 v[98:101], v[154:157], v[170:173], v[98:101]
	v_mfma_f32_16x16x32_bf16 v[78:81], v[146:149], v[178:181], v[78:81]
	v_mfma_f32_16x16x32_bf16 v[74:77], v[154:157], v[178:181], v[74:77]
	v_mfma_f32_16x16x32_bf16 v[70:73], v[146:149], v[186:189], v[70:73]
	v_mfma_f32_16x16x32_bf16 v[66:69], v[154:157], v[186:189], v[66:69]
	v_mfma_f32_16x16x32_bf16 v[118:121], v[150:153], v[166:169], v[118:121]
	v_mfma_f32_16x16x32_bf16 v[110:113], v[158:161], v[166:169], v[110:113]
	v_mfma_f32_16x16x32_bf16 v[102:105], v[150:153], v[174:177], v[102:105]
	v_mfma_f32_16x16x32_bf16 v[98:101], v[158:161], v[174:177], v[98:101]
	v_mfma_f32_16x16x32_bf16 v[78:81], v[150:153], v[182:185], v[78:81]
	v_mfma_f32_16x16x32_bf16 v[74:77], v[158:161], v[182:185], v[74:77]
	v_mfma_f32_16x16x32_bf16 v[70:73], v[150:153], v[190:193], v[70:73]
	v_mfma_f32_16x16x32_bf16 v[66:69], v[158:161], v[190:193], v[66:69]
	s_barrier
	s_setprio 0
	ds_read_b128 v[162:165], v247 offset:16384
	ds_read_b128 v[166:169], v247 offset:17408
	ds_read_b128 v[170:173], v247 offset:18432
	ds_read_b128 v[174:177], v247 offset:19456
	ds_read_b128 v[178:181], v247 offset:20480
	ds_read_b128 v[182:185], v247 offset:21504
	ds_read_b128 v[186:189], v247 offset:22528
	ds_read_b128 v[190:193], v247 offset:23552
	s_add_i32 s38, s38, s46
	v_lshl_add_u64 v[194:195], s[16:17], 0, v[222:223]
	s_mov_b32 m0, s38
	s_nop 0
	global_load_lds_dwordx4 v[194:195], off
	s_add_i32 m0, s38, 0x2000
	s_add_u32 s38, s16, 0x164000
	v_lshl_add_u64 v[196:197], s[16:17], 0, v[226:227]
	s_addc_u32 s39, s17, 0
	s_add_i32 s40, s40, s46
	global_load_lds_dwordx4 v[196:197], off
	v_lshl_add_u64 v[198:199], s[38:39], 0, v[222:223]
	s_mov_b32 m0, s40
	s_nop 0
	global_load_lds_dwordx4 v[198:199], off
	v_lshl_add_u64 v[198:199], s[38:39], 0, v[226:227]
	s_add_i32 m0, s40, 0x2000
	s_nop 0
	global_load_lds_dwordx4 v[198:199], off
	v_lshl_add_u64 v[198:199], s[18:19], 0, v[220:221]
	s_mov_b32 m0, s47
	s_nop 0
	global_load_lds_dwordx4 v[198:199], off
	v_lshl_add_u64 v[198:199], s[18:19], 0, v[224:225]
	s_mov_b32 m0, s74
	s_nop 0
	global_load_lds_dwordx4 v[198:199], off
	s_waitcnt vmcnt(8)
	s_waitcnt lgkmcnt(0)
	s_setprio 1
	s_barrier
	v_mfma_f32_16x16x32_bf16 v[62:65], v[130:133], v[162:165], v[62:65]
	v_mfma_f32_16x16x32_bf16 v[58:61], v[138:141], v[162:165], v[58:61]
	v_mfma_f32_16x16x32_bf16 v[54:57], v[130:133], v[170:173], v[54:57]
	v_mfma_f32_16x16x32_bf16 v[50:53], v[138:141], v[170:173], v[50:53]
	v_mfma_f32_16x16x32_bf16 v[30:33], v[130:133], v[178:181], v[30:33]
	v_mfma_f32_16x16x32_bf16 v[26:29], v[138:141], v[178:181], v[26:29]
	v_mfma_f32_16x16x32_bf16 v[22:25], v[130:133], v[186:189], v[22:25]
	v_mfma_f32_16x16x32_bf16 v[18:21], v[138:141], v[186:189], v[18:21]
	v_mfma_f32_16x16x32_bf16 v[62:65], v[134:137], v[166:169], v[62:65]
	v_mfma_f32_16x16x32_bf16 v[58:61], v[142:145], v[166:169], v[58:61]
	v_mfma_f32_16x16x32_bf16 v[54:57], v[134:137], v[174:177], v[54:57]
	v_mfma_f32_16x16x32_bf16 v[50:53], v[142:145], v[174:177], v[50:53]
	v_mfma_f32_16x16x32_bf16 v[30:33], v[134:137], v[182:185], v[30:33]
	v_mfma_f32_16x16x32_bf16 v[26:29], v[142:145], v[182:185], v[26:29]
	v_mfma_f32_16x16x32_bf16 v[22:25], v[134:137], v[190:193], v[22:25]
	v_mfma_f32_16x16x32_bf16 v[18:21], v[142:145], v[190:193], v[18:21]
	s_setprio 0
	s_setprio 1
	v_mfma_f32_16x16x32_bf16 v[46:49], v[146:149], v[162:165], v[46:49]
	v_mfma_f32_16x16x32_bf16 v[42:45], v[154:157], v[162:165], v[42:45]
	v_mfma_f32_16x16x32_bf16 v[38:41], v[146:149], v[170:173], v[38:41]
	v_mfma_f32_16x16x32_bf16 v[34:37], v[154:157], v[170:173], v[34:37]
	v_mfma_f32_16x16x32_bf16 v[14:17], v[146:149], v[178:181], v[14:17]
	v_mfma_f32_16x16x32_bf16 v[10:13], v[154:157], v[178:181], v[10:13]
	v_mfma_f32_16x16x32_bf16 v[6:9], v[146:149], v[186:189], v[6:9]
	v_mfma_f32_16x16x32_bf16 v[2:5], v[154:157], v[186:189], v[2:5]
	v_mfma_f32_16x16x32_bf16 v[46:49], v[150:153], v[166:169], v[46:49]
	v_mfma_f32_16x16x32_bf16 v[42:45], v[158:161], v[166:169], v[42:45]
	v_mfma_f32_16x16x32_bf16 v[38:41], v[150:153], v[174:177], v[38:41]
	v_mfma_f32_16x16x32_bf16 v[34:37], v[158:161], v[174:177], v[34:37]
	v_mfma_f32_16x16x32_bf16 v[14:17], v[150:153], v[182:185], v[14:17]
	v_mfma_f32_16x16x32_bf16 v[10:13], v[158:161], v[182:185], v[10:13]
	v_mfma_f32_16x16x32_bf16 v[6:9], v[150:153], v[190:193], v[6:9]
	v_mfma_f32_16x16x32_bf16 v[2:5], v[158:161], v[190:193], v[2:5]
	s_barrier
	s_setprio 0
	s_add_i32 s38, 0, 0x18000
	v_add_u32_e32 v0, s38, v246
	s_add_i32 s39, 0, 0x1c000
	ds_read_b128 v[130:133], v0
	ds_read_b128 v[134:137], v0 offset:1024
	ds_read_b128 v[138:141], v0 offset:2048
	ds_read_b128 v[142:145], v0 offset:3072
	v_add_u32_e32 v0, s39, v246
	ds_read_b128 v[146:149], v0
	ds_read_b128 v[150:153], v0 offset:1024
	ds_read_b128 v[154:157], v0 offset:2048
	ds_read_b128 v[158:161], v0 offset:3072
	ds_read_b128 v[162:165], v247 offset:32768
	ds_read_b128 v[166:169], v247 offset:33792
	ds_read_b128 v[170:173], v247 offset:34816
	ds_read_b128 v[174:177], v247 offset:35840
	ds_read_b128 v[178:181], v247 offset:36864
	ds_read_b128 v[182:185], v247 offset:37888
	ds_read_b128 v[186:189], v247 offset:38912
	ds_read_b128 v[190:193], v247 offset:39936
	s_add_u32 s18, s18, 0x4000
	s_addc_u32 s19, s19, 0
	s_mov_b32 m0, s75
	v_lshl_add_u64 v[198:199], s[18:19], 0, v[220:221]
	global_load_lds_dwordx4 v[198:199], off
	v_lshl_add_u64 v[198:199], s[18:19], 0, v[224:225]
	s_mov_b32 m0, s86
	s_nop 0
	global_load_lds_dwordx4 v[198:199], off
	s_waitcnt vmcnt(8)
	s_waitcnt lgkmcnt(0)
	s_setprio 1
	s_barrier
	v_mfma_f32_16x16x32_bf16 v[126:129], v[130:133], v[162:165], v[126:129]
	v_mfma_f32_16x16x32_bf16 v[122:125], v[138:141], v[162:165], v[122:125]
	v_mfma_f32_16x16x32_bf16 v[114:117], v[130:133], v[170:173], v[114:117]
	v_mfma_f32_16x16x32_bf16 v[106:109], v[138:141], v[170:173], v[106:109]
	v_mfma_f32_16x16x32_bf16 v[94:97], v[130:133], v[178:181], v[94:97]
	v_mfma_f32_16x16x32_bf16 v[90:93], v[138:141], v[178:181], v[90:93]
	v_mfma_f32_16x16x32_bf16 v[86:89], v[130:133], v[186:189], v[86:89]
	v_mfma_f32_16x16x32_bf16 v[82:85], v[138:141], v[186:189], v[82:85]
	v_mfma_f32_16x16x32_bf16 v[126:129], v[134:137], v[166:169], v[126:129]
	v_mfma_f32_16x16x32_bf16 v[122:125], v[142:145], v[166:169], v[122:125]
	v_mfma_f32_16x16x32_bf16 v[114:117], v[134:137], v[174:177], v[114:117]
	v_mfma_f32_16x16x32_bf16 v[106:109], v[142:145], v[174:177], v[106:109]
	v_mfma_f32_16x16x32_bf16 v[94:97], v[134:137], v[182:185], v[94:97]
	v_mfma_f32_16x16x32_bf16 v[90:93], v[142:145], v[182:185], v[90:93]
	v_mfma_f32_16x16x32_bf16 v[86:89], v[134:137], v[190:193], v[86:89]
	v_mfma_f32_16x16x32_bf16 v[82:85], v[142:145], v[190:193], v[82:85]
	s_setprio 0
	s_setprio 1
	v_mfma_f32_16x16x32_bf16 v[118:121], v[146:149], v[162:165], v[118:121]
	v_mfma_f32_16x16x32_bf16 v[110:113], v[154:157], v[162:165], v[110:113]
	v_mfma_f32_16x16x32_bf16 v[102:105], v[146:149], v[170:173], v[102:105]
	v_mfma_f32_16x16x32_bf16 v[98:101], v[154:157], v[170:173], v[98:101]
	v_mfma_f32_16x16x32_bf16 v[78:81], v[146:149], v[178:181], v[78:81]
	v_mfma_f32_16x16x32_bf16 v[74:77], v[154:157], v[178:181], v[74:77]
	v_mfma_f32_16x16x32_bf16 v[70:73], v[146:149], v[186:189], v[70:73]
	v_mfma_f32_16x16x32_bf16 v[66:69], v[154:157], v[186:189], v[66:69]
	v_mfma_f32_16x16x32_bf16 v[118:121], v[150:153], v[166:169], v[118:121]
	v_mfma_f32_16x16x32_bf16 v[110:113], v[158:161], v[166:169], v[110:113]
	v_mfma_f32_16x16x32_bf16 v[102:105], v[150:153], v[174:177], v[102:105]
	v_mfma_f32_16x16x32_bf16 v[98:101], v[158:161], v[174:177], v[98:101]
	v_mfma_f32_16x16x32_bf16 v[78:81], v[150:153], v[182:185], v[78:81]
	v_mfma_f32_16x16x32_bf16 v[74:77], v[158:161], v[182:185], v[74:77]
	v_mfma_f32_16x16x32_bf16 v[70:73], v[150:153], v[190:193], v[70:73]
	v_mfma_f32_16x16x32_bf16 v[66:69], v[158:161], v[190:193], v[66:69]
	s_barrier
	s_setprio 0
	ds_read_b128 v[162:165], v247 offset:49152
	ds_read_b128 v[166:169], v247 offset:50176
	ds_read_b128 v[170:173], v247 offset:51200
	ds_read_b128 v[174:177], v247 offset:52224
	ds_read_b128 v[178:181], v247 offset:53248
	ds_read_b128 v[182:185], v247 offset:54272
	ds_read_b128 v[186:189], v247 offset:55296
	ds_read_b128 v[190:193], v247 offset:56320
	s_add_i32 s18, s38, s46
	v_lshl_add_u64 v[194:195], v[194:195], 0, s[2:3]
	s_mov_b32 m0, s18
	s_nop 0
	global_load_lds_dwordx4 v[194:195], off
	s_add_i32 m0, s18, 0x2000
	s_add_u32 s16, s16, 0x164080
	v_lshl_add_u64 v[194:195], v[196:197], 0, s[2:3]
	s_addc_u32 s17, s17, 0
	s_add_i32 s18, s39, s46
	global_load_lds_dwordx4 v[194:195], off
	v_lshl_add_u64 v[194:195], s[16:17], 0, v[222:223]
	s_mov_b32 m0, s18
	s_nop 0
	global_load_lds_dwordx4 v[194:195], off
	v_lshl_add_u64 v[194:195], s[16:17], 0, v[226:227]
	s_add_i32 m0, s18, 0x2000
	s_nop 0
	global_load_lds_dwordx4 v[194:195], off
	v_lshl_add_u64 v[194:195], s[14:15], 0, v[220:221]
	s_mov_b32 m0, s50
	s_nop 0
	global_load_lds_dwordx4 v[194:195], off
	v_lshl_add_u64 v[194:195], s[14:15], 0, v[224:225]
	s_mov_b32 m0, s51
	s_nop 0
	global_load_lds_dwordx4 v[194:195], off
	s_waitcnt vmcnt(8)
	s_waitcnt lgkmcnt(0)
	s_setprio 1
	s_barrier
	v_mfma_f32_16x16x32_bf16 v[62:65], v[130:133], v[162:165], v[62:65]
	v_mfma_f32_16x16x32_bf16 v[58:61], v[138:141], v[162:165], v[58:61]
	v_mfma_f32_16x16x32_bf16 v[54:57], v[130:133], v[170:173], v[54:57]
	v_mfma_f32_16x16x32_bf16 v[50:53], v[138:141], v[170:173], v[50:53]
	v_mfma_f32_16x16x32_bf16 v[30:33], v[130:133], v[178:181], v[30:33]
	v_mfma_f32_16x16x32_bf16 v[26:29], v[138:141], v[178:181], v[26:29]
	v_mfma_f32_16x16x32_bf16 v[22:25], v[130:133], v[186:189], v[22:25]
	v_mfma_f32_16x16x32_bf16 v[18:21], v[138:141], v[186:189], v[18:21]
	v_mfma_f32_16x16x32_bf16 v[62:65], v[134:137], v[166:169], v[62:65]
	v_mfma_f32_16x16x32_bf16 v[58:61], v[142:145], v[166:169], v[58:61]
	v_mfma_f32_16x16x32_bf16 v[54:57], v[134:137], v[174:177], v[54:57]
	v_mfma_f32_16x16x32_bf16 v[50:53], v[142:145], v[174:177], v[50:53]
	v_mfma_f32_16x16x32_bf16 v[30:33], v[134:137], v[182:185], v[30:33]
	v_mfma_f32_16x16x32_bf16 v[26:29], v[142:145], v[182:185], v[26:29]
	v_mfma_f32_16x16x32_bf16 v[22:25], v[134:137], v[190:193], v[22:25]
	v_mfma_f32_16x16x32_bf16 v[18:21], v[142:145], v[190:193], v[18:21]
	s_setprio 0
	s_setprio 1
	v_mfma_f32_16x16x32_bf16 v[46:49], v[146:149], v[162:165], v[46:49]
	v_mfma_f32_16x16x32_bf16 v[42:45], v[154:157], v[162:165], v[42:45]
	v_mfma_f32_16x16x32_bf16 v[38:41], v[146:149], v[170:173], v[38:41]
	v_mfma_f32_16x16x32_bf16 v[34:37], v[154:157], v[170:173], v[34:37]
	v_mfma_f32_16x16x32_bf16 v[14:17], v[146:149], v[178:181], v[14:17]
	v_mfma_f32_16x16x32_bf16 v[10:13], v[154:157], v[178:181], v[10:13]
	v_mfma_f32_16x16x32_bf16 v[6:9], v[146:149], v[186:189], v[6:9]
	v_mfma_f32_16x16x32_bf16 v[2:5], v[154:157], v[186:189], v[2:5]
	v_mfma_f32_16x16x32_bf16 v[46:49], v[150:153], v[166:169], v[46:49]
	v_mfma_f32_16x16x32_bf16 v[42:45], v[158:161], v[166:169], v[42:45]
	v_mfma_f32_16x16x32_bf16 v[38:41], v[150:153], v[174:177], v[38:41]
	v_mfma_f32_16x16x32_bf16 v[34:37], v[158:161], v[174:177], v[34:37]
	v_mfma_f32_16x16x32_bf16 v[14:17], v[150:153], v[182:185], v[14:17]
	v_mfma_f32_16x16x32_bf16 v[10:13], v[158:161], v[182:185], v[10:13]
	v_mfma_f32_16x16x32_bf16 v[6:9], v[150:153], v[190:193], v[6:9]
	v_mfma_f32_16x16x32_bf16 v[2:5], v[158:161], v[190:193], v[2:5]
	s_barrier
	s_setprio 0
	s_add_i32 s37, s37, 2
	s_add_u32 s11, s11, 0x100
	s_addc_u32 s36, s36, 0
	s_add_u32 s12, s12, 0x10000
	s_addc_u32 s13, s13, 0
	s_cmpk_gt_u32 s37, 0x55
	s_cbranch_scc0 .LBB0_1844

.LBB0_2017:
	s_add_i32 s51, 0, 0x10000
	s_add_i32 s54, 0, 0x14000
	v_add_u32_e32 v156, s51, v140
	v_add_u32_e32 v172, s54, v140
	ds_read_b128 v[144:147], v156
	ds_read_b128 v[148:151], v156 offset:1024
	ds_read_b128 v[152:155], v156 offset:2048
	ds_read_b128 v[156:159], v156 offset:3072
	ds_read_b128 v[160:163], v172
	ds_read_b128 v[164:167], v172 offset:1024
	ds_read_b128 v[168:171], v172 offset:2048
	ds_read_b128 v[172:175], v172 offset:3072
	ds_read_b128 v[176:179], v143
	ds_read_b128 v[180:183], v143 offset:1024
	ds_read_b128 v[184:187], v143 offset:2048
	ds_read_b128 v[188:191], v143 offset:3072
	ds_read_b128 v[192:195], v143 offset:4096
	ds_read_b128 v[196:199], v143 offset:5120
	ds_read_b128 v[200:203], v143 offset:6144
	ds_read_b128 v[204:207], v143 offset:7168
	s_add_u32 s14, s12, 0x4000
	s_addc_u32 s15, s13, 0
	s_cmp_eq_u32 s50, 18
	s_cselect_b32 s18, s8, s14
	s_cselect_b32 s19, s9, s15
	s_cselect_b32 s16, s10, s36
	s_cselect_b32 s17, s11, s37
	s_add_u32 s14, s18, 0x8000
	s_addc_u32 s15, s19, 0
	v_lshl_add_u64 v[208:209], s[12:13], 0, v[136:137]
	s_add_i32 m0, s38, 0xc000
	s_nop 0
	global_load_lds_dwordx4 v[208:209], off
	v_lshl_add_u64 v[208:209], s[12:13], 0, v[138:139]
	s_add_i32 m0, s38, 0xe000
	s_nop 0
	global_load_lds_dwordx4 v[208:209], off
	s_waitcnt vmcnt(8)
	s_waitcnt lgkmcnt(0)
	s_setprio 1
	s_barrier
	v_mfma_f32_16x16x32_bf16 v[126:129], v[144:147], v[176:179], v[126:129]
	v_mfma_f32_16x16x32_bf16 v[122:125], v[152:155], v[176:179], v[122:125]
	v_mfma_f32_16x16x32_bf16 v[118:121], v[144:147], v[184:187], v[118:121]
	v_mfma_f32_16x16x32_bf16 v[114:117], v[152:155], v[184:187], v[114:117]
	v_mfma_f32_16x16x32_bf16 v[102:105], v[144:147], v[192:195], v[102:105]
	v_mfma_f32_16x16x32_bf16 v[98:101], v[152:155], v[192:195], v[98:101]
	v_mfma_f32_16x16x32_bf16 v[86:89], v[144:147], v[200:203], v[86:89]
	v_mfma_f32_16x16x32_bf16 v[82:85], v[152:155], v[200:203], v[82:85]
	v_mfma_f32_16x16x32_bf16 v[126:129], v[148:151], v[180:183], v[126:129]
	v_mfma_f32_16x16x32_bf16 v[122:125], v[156:159], v[180:183], v[122:125]
	v_mfma_f32_16x16x32_bf16 v[118:121], v[148:151], v[188:191], v[118:121]
	v_mfma_f32_16x16x32_bf16 v[114:117], v[156:159], v[188:191], v[114:117]
	v_mfma_f32_16x16x32_bf16 v[102:105], v[148:151], v[196:199], v[102:105]
	v_mfma_f32_16x16x32_bf16 v[98:101], v[156:159], v[196:199], v[98:101]
	v_mfma_f32_16x16x32_bf16 v[86:89], v[148:151], v[204:207], v[86:89]
	v_mfma_f32_16x16x32_bf16 v[82:85], v[156:159], v[204:207], v[82:85]
	s_setprio 0
	s_setprio 1
	v_mfma_f32_16x16x32_bf16 v[110:113], v[160:163], v[176:179], v[110:113]
	v_mfma_f32_16x16x32_bf16 v[106:109], v[168:171], v[176:179], v[106:109]
	v_mfma_f32_16x16x32_bf16 v[94:97], v[160:163], v[184:187], v[94:97]
	v_mfma_f32_16x16x32_bf16 v[90:93], v[168:171], v[184:187], v[90:93]
	v_mfma_f32_16x16x32_bf16 v[78:81], v[160:163], v[192:195], v[78:81]
	v_mfma_f32_16x16x32_bf16 v[74:77], v[168:171], v[192:195], v[74:77]
	v_mfma_f32_16x16x32_bf16 v[70:73], v[160:163], v[200:203], v[70:73]
	v_mfma_f32_16x16x32_bf16 v[66:69], v[168:171], v[200:203], v[66:69]
	v_mfma_f32_16x16x32_bf16 v[110:113], v[164:167], v[180:183], v[110:113]
	v_mfma_f32_16x16x32_bf16 v[106:109], v[172:175], v[180:183], v[106:109]
	v_mfma_f32_16x16x32_bf16 v[94:97], v[164:167], v[188:191], v[94:97]
	v_mfma_f32_16x16x32_bf16 v[90:93], v[172:175], v[188:191], v[90:93]
	v_mfma_f32_16x16x32_bf16 v[78:81], v[164:167], v[196:199], v[78:81]
	v_mfma_f32_16x16x32_bf16 v[74:77], v[172:175], v[196:199], v[74:77]
	v_mfma_f32_16x16x32_bf16 v[70:73], v[164:167], v[204:207], v[70:73]
	v_mfma_f32_16x16x32_bf16 v[66:69], v[172:175], v[204:207], v[66:69]
	s_barrier
	s_setprio 0
	ds_read_b128 v[176:179], v143 offset:16384
	ds_read_b128 v[180:183], v143 offset:17408
	ds_read_b128 v[184:187], v143 offset:18432
	ds_read_b128 v[188:191], v143 offset:19456
	ds_read_b128 v[192:195], v143 offset:20480
	ds_read_b128 v[196:199], v143 offset:21504
	ds_read_b128 v[200:203], v143 offset:22528
	ds_read_b128 v[204:207], v143 offset:23552
	s_add_i32 s51, s51, s24
	v_lshl_add_u64 v[208:209], s[16:17], 0, v[0:1]
	s_mov_b32 m0, s51
	s_nop 0
	global_load_lds_dwordx4 v[208:209], off
	s_add_i32 m0, s51, 0x2000
	s_add_u32 s52, s16, 0x164000
	v_lshl_add_u64 v[216:217], s[16:17], 0, v[130:131]
	s_addc_u32 s53, s17, 0
	s_add_i32 s51, s54, s24
	global_load_lds_dwordx4 v[216:217], off
	v_lshl_add_u64 v[220:221], s[52:53], 0, v[0:1]
	s_mov_b32 m0, s51
	s_nop 0
	global_load_lds_dwordx4 v[220:221], off
	v_lshl_add_u64 v[220:221], s[52:53], 0, v[130:131]
	s_add_i32 m0, s51, 0x2000
	s_nop 0
	global_load_lds_dwordx4 v[220:221], off
	v_lshl_add_u64 v[220:221], s[18:19], 0, v[134:135]
	s_mov_b32 m0, s38
	s_nop 0
	global_load_lds_dwordx4 v[220:221], off
	v_lshl_add_u64 v[220:221], s[18:19], 0, v[132:133]
	s_mov_b32 m0, s39
	s_nop 0
	global_load_lds_dwordx4 v[220:221], off
	s_waitcnt vmcnt(8)
	s_waitcnt lgkmcnt(0)
	s_setprio 1
	s_barrier
	v_mfma_f32_16x16x32_bf16 v[62:65], v[144:147], v[176:179], v[62:65]
	v_mfma_f32_16x16x32_bf16 v[58:61], v[152:155], v[176:179], v[58:61]
	v_mfma_f32_16x16x32_bf16 v[54:57], v[144:147], v[184:187], v[54:57]
	v_mfma_f32_16x16x32_bf16 v[50:53], v[152:155], v[184:187], v[50:53]
	v_mfma_f32_16x16x32_bf16 v[38:41], v[144:147], v[192:195], v[38:41]
	v_mfma_f32_16x16x32_bf16 v[34:37], v[152:155], v[192:195], v[34:37]
	v_mfma_f32_16x16x32_bf16 v[22:25], v[144:147], v[200:203], v[22:25]
	v_mfma_f32_16x16x32_bf16 v[18:21], v[152:155], v[200:203], v[18:21]
	v_mfma_f32_16x16x32_bf16 v[62:65], v[148:151], v[180:183], v[62:65]
	v_mfma_f32_16x16x32_bf16 v[58:61], v[156:159], v[180:183], v[58:61]
	v_mfma_f32_16x16x32_bf16 v[54:57], v[148:151], v[188:191], v[54:57]
	v_mfma_f32_16x16x32_bf16 v[50:53], v[156:159], v[188:191], v[50:53]
	v_mfma_f32_16x16x32_bf16 v[38:41], v[148:151], v[196:199], v[38:41]
	v_mfma_f32_16x16x32_bf16 v[34:37], v[156:159], v[196:199], v[34:37]
	v_mfma_f32_16x16x32_bf16 v[22:25], v[148:151], v[204:207], v[22:25]
	v_mfma_f32_16x16x32_bf16 v[18:21], v[156:159], v[204:207], v[18:21]
	s_setprio 0
	s_setprio 1
	v_mfma_f32_16x16x32_bf16 v[46:49], v[160:163], v[176:179], v[46:49]
	v_mfma_f32_16x16x32_bf16 v[42:45], v[168:171], v[176:179], v[42:45]
	v_mfma_f32_16x16x32_bf16 v[30:33], v[160:163], v[184:187], v[30:33]
	v_mfma_f32_16x16x32_bf16 v[26:29], v[168:171], v[184:187], v[26:29]
	v_mfma_f32_16x16x32_bf16 v[14:17], v[160:163], v[192:195], v[14:17]
	v_mfma_f32_16x16x32_bf16 v[10:13], v[168:171], v[192:195], v[10:13]
	v_mfma_f32_16x16x32_bf16 v[6:9], v[160:163], v[200:203], v[6:9]
	v_mfma_f32_16x16x32_bf16 v[2:5], v[168:171], v[200:203], v[2:5]
	v_mfma_f32_16x16x32_bf16 v[46:49], v[164:167], v[180:183], v[46:49]
	v_mfma_f32_16x16x32_bf16 v[42:45], v[172:175], v[180:183], v[42:45]
	v_mfma_f32_16x16x32_bf16 v[30:33], v[164:167], v[188:191], v[30:33]
	v_mfma_f32_16x16x32_bf16 v[26:29], v[172:175], v[188:191], v[26:29]
	v_mfma_f32_16x16x32_bf16 v[14:17], v[164:167], v[196:199], v[14:17]
	v_mfma_f32_16x16x32_bf16 v[10:13], v[172:175], v[196:199], v[10:13]
	v_mfma_f32_16x16x32_bf16 v[6:9], v[164:167], v[204:207], v[6:9]
	v_mfma_f32_16x16x32_bf16 v[2:5], v[172:175], v[204:207], v[2:5]
	s_barrier
	s_setprio 0
	s_add_i32 s51, 0, 0x18000
	s_add_i32 s52, 0, 0x1c000
	v_add_u32_e32 v156, s51, v140
	v_add_u32_e32 v172, s52, v140
	ds_read_b128 v[144:147], v156
	ds_read_b128 v[148:151], v156 offset:1024
	ds_read_b128 v[152:155], v156 offset:2048
	ds_read_b128 v[156:159], v156 offset:3072
	ds_read_b128 v[160:163], v172
	ds_read_b128 v[164:167], v172 offset:1024
	ds_read_b128 v[168:171], v172 offset:2048
	ds_read_b128 v[172:175], v172 offset:3072
	ds_read_b128 v[176:179], v143 offset:32768
	ds_read_b128 v[180:183], v143 offset:33792
	ds_read_b128 v[184:187], v143 offset:34816
	ds_read_b128 v[188:191], v143 offset:35840
	ds_read_b128 v[192:195], v143 offset:36864
	ds_read_b128 v[196:199], v143 offset:37888
	ds_read_b128 v[200:203], v143 offset:38912
	ds_read_b128 v[204:207], v143 offset:39936
	s_add_u32 s18, s18, 0x4000
	s_addc_u32 s19, s19, 0
	s_mov_b32 m0, s40
	v_lshl_add_u64 v[220:221], s[18:19], 0, v[134:135]
	global_load_lds_dwordx4 v[220:221], off
	v_lshl_add_u64 v[220:221], s[18:19], 0, v[132:133]
	s_mov_b32 m0, s41
	s_nop 0
	global_load_lds_dwordx4 v[220:221], off
	s_waitcnt vmcnt(8)
	s_waitcnt lgkmcnt(0)
	s_setprio 1
	s_barrier
	v_mfma_f32_16x16x32_bf16 v[126:129], v[144:147], v[176:179], v[126:129]
	v_mfma_f32_16x16x32_bf16 v[122:125], v[152:155], v[176:179], v[122:125]
	v_mfma_f32_16x16x32_bf16 v[118:121], v[144:147], v[184:187], v[118:121]
	v_mfma_f32_16x16x32_bf16 v[114:117], v[152:155], v[184:187], v[114:117]
	v_mfma_f32_16x16x32_bf16 v[102:105], v[144:147], v[192:195], v[102:105]
	v_mfma_f32_16x16x32_bf16 v[98:101], v[152:155], v[192:195], v[98:101]
	v_mfma_f32_16x16x32_bf16 v[86:89], v[144:147], v[200:203], v[86:89]
	v_mfma_f32_16x16x32_bf16 v[82:85], v[152:155], v[200:203], v[82:85]
	v_mfma_f32_16x16x32_bf16 v[126:129], v[148:151], v[180:183], v[126:129]
	v_mfma_f32_16x16x32_bf16 v[122:125], v[156:159], v[180:183], v[122:125]
	v_mfma_f32_16x16x32_bf16 v[118:121], v[148:151], v[188:191], v[118:121]
	v_mfma_f32_16x16x32_bf16 v[114:117], v[156:159], v[188:191], v[114:117]
	v_mfma_f32_16x16x32_bf16 v[102:105], v[148:151], v[196:199], v[102:105]
	v_mfma_f32_16x16x32_bf16 v[98:101], v[156:159], v[196:199], v[98:101]
	v_mfma_f32_16x16x32_bf16 v[86:89], v[148:151], v[204:207], v[86:89]
	v_mfma_f32_16x16x32_bf16 v[82:85], v[156:159], v[204:207], v[82:85]
	s_setprio 0
	s_setprio 1
	v_mfma_f32_16x16x32_bf16 v[110:113], v[160:163], v[176:179], v[110:113]
	v_mfma_f32_16x16x32_bf16 v[106:109], v[168:171], v[176:179], v[106:109]
	v_mfma_f32_16x16x32_bf16 v[94:97], v[160:163], v[184:187], v[94:97]
	v_mfma_f32_16x16x32_bf16 v[90:93], v[168:171], v[184:187], v[90:93]
	v_mfma_f32_16x16x32_bf16 v[78:81], v[160:163], v[192:195], v[78:81]
	v_mfma_f32_16x16x32_bf16 v[74:77], v[168:171], v[192:195], v[74:77]
	v_mfma_f32_16x16x32_bf16 v[70:73], v[160:163], v[200:203], v[70:73]
	v_mfma_f32_16x16x32_bf16 v[66:69], v[168:171], v[200:203], v[66:69]
	v_mfma_f32_16x16x32_bf16 v[110:113], v[164:167], v[180:183], v[110:113]
	v_mfma_f32_16x16x32_bf16 v[106:109], v[172:175], v[180:183], v[106:109]
	v_mfma_f32_16x16x32_bf16 v[94:97], v[164:167], v[188:191], v[94:97]
	v_mfma_f32_16x16x32_bf16 v[90:93], v[172:175], v[188:191], v[90:93]
	v_mfma_f32_16x16x32_bf16 v[78:81], v[164:167], v[196:199], v[78:81]
	v_mfma_f32_16x16x32_bf16 v[74:77], v[172:175], v[196:199], v[74:77]
	v_mfma_f32_16x16x32_bf16 v[70:73], v[164:167], v[204:207], v[70:73]
	v_mfma_f32_16x16x32_bf16 v[66:69], v[172:175], v[204:207], v[66:69]
	s_barrier
	s_setprio 0
	ds_read_b128 v[176:179], v143 offset:49152
	ds_read_b128 v[180:183], v143 offset:50176
	ds_read_b128 v[184:187], v143 offset:51200
	ds_read_b128 v[188:191], v143 offset:52224
	ds_read_b128 v[192:195], v143 offset:53248
	ds_read_b128 v[196:199], v143 offset:54272
	ds_read_b128 v[200:203], v143 offset:55296
	ds_read_b128 v[204:207], v143 offset:56320
	s_add_i32 s18, s51, s24
	v_lshl_add_u64 v[208:209], v[208:209], 0, s[2:3]
	s_mov_b32 m0, s18
	s_nop 0
	global_load_lds_dwordx4 v[208:209], off
	s_add_i32 m0, s18, 0x2000
	s_add_u32 s16, s16, 0x164080
	v_lshl_add_u64 v[208:209], v[216:217], 0, s[2:3]
	s_addc_u32 s17, s17, 0
	s_add_i32 s18, s52, s24
	global_load_lds_dwordx4 v[208:209], off
	v_lshl_add_u64 v[208:209], s[16:17], 0, v[0:1]
	s_mov_b32 m0, s18
	s_nop 0
	global_load_lds_dwordx4 v[208:209], off
	v_lshl_add_u64 v[208:209], s[16:17], 0, v[130:131]
	s_add_i32 m0, s18, 0x2000
	s_nop 0
	global_load_lds_dwordx4 v[208:209], off
	v_lshl_add_u64 v[208:209], s[14:15], 0, v[134:135]
	s_mov_b32 m0, s42
	s_nop 0
	global_load_lds_dwordx4 v[208:209], off
	v_lshl_add_u64 v[208:209], s[14:15], 0, v[132:133]
	s_mov_b32 m0, s43
	s_nop 0
	global_load_lds_dwordx4 v[208:209], off
	s_waitcnt vmcnt(8)
	s_waitcnt lgkmcnt(0)
	s_setprio 1
	s_barrier
	v_mfma_f32_16x16x32_bf16 v[62:65], v[144:147], v[176:179], v[62:65]
	v_mfma_f32_16x16x32_bf16 v[58:61], v[152:155], v[176:179], v[58:61]
	v_mfma_f32_16x16x32_bf16 v[54:57], v[144:147], v[184:187], v[54:57]
	v_mfma_f32_16x16x32_bf16 v[50:53], v[152:155], v[184:187], v[50:53]
	v_mfma_f32_16x16x32_bf16 v[38:41], v[144:147], v[192:195], v[38:41]
	v_mfma_f32_16x16x32_bf16 v[34:37], v[152:155], v[192:195], v[34:37]
	v_mfma_f32_16x16x32_bf16 v[22:25], v[144:147], v[200:203], v[22:25]
	v_mfma_f32_16x16x32_bf16 v[18:21], v[152:155], v[200:203], v[18:21]
	v_mfma_f32_16x16x32_bf16 v[62:65], v[148:151], v[180:183], v[62:65]
	v_mfma_f32_16x16x32_bf16 v[58:61], v[156:159], v[180:183], v[58:61]
	v_mfma_f32_16x16x32_bf16 v[54:57], v[148:151], v[188:191], v[54:57]
	v_mfma_f32_16x16x32_bf16 v[50:53], v[156:159], v[188:191], v[50:53]
	v_mfma_f32_16x16x32_bf16 v[38:41], v[148:151], v[196:199], v[38:41]
	v_mfma_f32_16x16x32_bf16 v[34:37], v[156:159], v[196:199], v[34:37]
	v_mfma_f32_16x16x32_bf16 v[22:25], v[148:151], v[204:207], v[22:25]
	v_mfma_f32_16x16x32_bf16 v[18:21], v[156:159], v[204:207], v[18:21]
	s_setprio 0
	s_setprio 1
	v_mfma_f32_16x16x32_bf16 v[46:49], v[160:163], v[176:179], v[46:49]
	v_mfma_f32_16x16x32_bf16 v[42:45], v[168:171], v[176:179], v[42:45]
	v_mfma_f32_16x16x32_bf16 v[30:33], v[160:163], v[184:187], v[30:33]
	v_mfma_f32_16x16x32_bf16 v[26:29], v[168:171], v[184:187], v[26:29]
	v_mfma_f32_16x16x32_bf16 v[14:17], v[160:163], v[192:195], v[14:17]
	v_mfma_f32_16x16x32_bf16 v[10:13], v[168:171], v[192:195], v[10:13]
	v_mfma_f32_16x16x32_bf16 v[6:9], v[160:163], v[200:203], v[6:9]
	v_mfma_f32_16x16x32_bf16 v[2:5], v[168:171], v[200:203], v[2:5]
	v_mfma_f32_16x16x32_bf16 v[46:49], v[164:167], v[180:183], v[46:49]
	v_mfma_f32_16x16x32_bf16 v[42:45], v[172:175], v[180:183], v[42:45]
	v_mfma_f32_16x16x32_bf16 v[30:33], v[164:167], v[188:191], v[30:33]
	v_mfma_f32_16x16x32_bf16 v[26:29], v[172:175], v[188:191], v[26:29]
	v_mfma_f32_16x16x32_bf16 v[14:17], v[164:167], v[196:199], v[14:17]
	v_mfma_f32_16x16x32_bf16 v[10:13], v[172:175], v[196:199], v[10:13]
	v_mfma_f32_16x16x32_bf16 v[6:9], v[164:167], v[204:207], v[6:9]
	v_mfma_f32_16x16x32_bf16 v[2:5], v[172:175], v[204:207], v[2:5]
	s_barrier
	s_setprio 0
	s_add_i32 s50, s50, 2
	s_add_u32 s36, s36, 0x100
	s_addc_u32 s37, s37, 0
	s_add_u32 s12, s12, 0x10000
	s_addc_u32 s13, s13, 0
	s_cmp_gt_u32 s50, 19
	s_cbranch_scc0 .LBB0_2017
